# GEMM MMA phases: independent MFMAs re-ordered so consecutive MFMAs change only one matrix operand (snake), bit-identical (on pack_more)
# baseline (speedup 1.0000x reference)
; #define PG8_STAGE(bufoff, gbase, voff) glds16s2((voff)[0], (voff)[1], (const void*)(gbase), ldsn + (unsigned)(bufoff))
; #define PG8_LDA(dst, b, h) do { _Pragma("unroll") for (int m = 0; m < 4; ++m) _Pragma("unroll") for (int k = 0; k < 2; ++k) dst[m][k] = *(const LAS bf16x8*)(lds + PG8_SA(b, h) + aoff + m * 2048 + k * 1024); } while (0)
; #define PG8_LDB(dst, b, h) do { _Pragma("unroll") for (int n = 0; n < 2; ++n) _Pragma("unroll") for (int k = 0; k < 2; ++k) dst[n][k] = *(const LAS bf16x8*)(lds + PG8_SB(b, h) + boff + n * 2048 + k * 1024); } while (0)
; #define PG8_MMA(ai, bj, At, Bt) do { __builtin_amdgcn_s_setprio(1); _Pragma("unroll") for (int m = 0; m < 4; ++m) _Pragma("unroll") for (int n = 0; n < 2; ++n) _Pragma("unroll") for (int k = 0; k < 2; ++k) \
;         acc[ai][bj][m][n] = __builtin_amdgcn_mfma_f32_16x16x32_bf16(Bt[n][k], At[m][k], acc[ai][bj][m][n], 0, 0, 0); __builtin_amdgcn_s_setprio(0); } while (0)
; #define PG8_WAIT_V(n) asm volatile("s_waitcnt vmcnt(" #n ")" ::: "memory")
; #define PG8_WAIT_L(n) asm volatile("s_waitcnt lgkmcnt(" #n ")" ::: "memory")
; #define PG8_BAR __builtin_amdgcn_s_barrier()
; #define PG8_SCHED __builtin_amdgcn_sched_barrier(0)
; template <class Epi, bool ALIGN_EPI, bool EARLY_DRAIN = true, class Pre = NoPre>
; __device__ __forceinline__ void gemm_phase(LAS unsigned char* lds, const Gemm g, const StaticOrder& S, const Epi& E, int wv, const Pre& pre = Pre()) {
;     ...
;             PG8_LDB(B0, 0, 0); PG8_LDB(B1, 0, 1); PG8_SCHED; PG8_LDA(At, 0, 0); PG8_STAGE(PG8_SA(1, 1), a1 + ahs, voffA);
;             if (!lf_) PG8_WAIT_V(8);
;             PG8_WAIT_L(0); PG8_BAR; PG8_MMA(0, 0, At, B0); PG8_MMA(0, 1, At, B1); PG8_BAR; PG8_SCHED;
;             PG8_LDA(At, 0, 1); PG8_STAGE(PG8_SB(0, 0), b2, voffB); PG8_STAGE(PG8_SB(0, 1), b2 + bhs, voffB); PG8_STAGE(PG8_SA(0, 0), a2, voffA);
;             if (!lf_) PG8_WAIT_V(8);
.LBB0_172:
	s_add_u32 s50, s70, 0x100
	s_addc_u32 s51, s71, 0
	s_waitcnt lgkmcnt(0)
	s_add_u32 s38, s68, 0x100
	s_addc_u32 s39, s69, 0
	s_barrier
	s_setprio 1
	s_waitcnt lgkmcnt(7)
	v_mfma_f32_16x16x32_bf16 v[2:5], v[86:89], v[38:41], 0
	v_mfma_f32_16x16x32_bf16 v[6:9], v[94:97], v[38:41], 0
	s_waitcnt lgkmcnt(5)
	v_mfma_f32_16x16x32_bf16 v[10:13], v[86:89], v[46:49], 0
	v_mfma_f32_16x16x32_bf16 v[14:17], v[94:97], v[46:49], 0
	s_waitcnt lgkmcnt(3)
	v_mfma_f32_16x16x32_bf16 v[18:21], v[86:89], v[58:61], 0
	v_mfma_f32_16x16x32_bf16 v[22:25], v[94:97], v[58:61], 0
	s_waitcnt lgkmcnt(1)
	v_mfma_f32_16x16x32_bf16 v[26:29], v[86:89], v[74:77], 0
	v_mfma_f32_16x16x32_bf16 v[30:33], v[94:97], v[74:77], 0
	v_mfma_f32_16x16x32_bf16 v[2:5], v[90:93], v[42:45], v[2:5]
	v_mfma_f32_16x16x32_bf16 v[6:9], v[98:101], v[42:45], v[6:9]
	v_mfma_f32_16x16x32_bf16 v[14:17], v[98:101], v[54:57], v[14:17]
	v_mfma_f32_16x16x32_bf16 v[10:13], v[90:93], v[54:57], v[10:13]
	v_mfma_f32_16x16x32_bf16 v[18:21], v[90:93], v[66:69], v[18:21]
	v_mfma_f32_16x16x32_bf16 v[22:25], v[98:101], v[66:69], v[22:25]
	s_waitcnt lgkmcnt(0)
	v_mfma_f32_16x16x32_bf16 v[30:33], v[98:101], v[78:81], v[30:33]
	v_mfma_f32_16x16x32_bf16 v[26:29], v[90:93], v[78:81], v[26:29]
	s_setprio 0
	s_setprio 1
	v_mfma_f32_16x16x32_bf16 v[34:37], v[50:53], v[38:41], 0
	v_mfma_f32_16x16x32_bf16 v[38:41], v[70:73], v[38:41], 0
	v_mfma_f32_16x16x32_bf16 v[34:37], v[62:65], v[42:45], v[34:37]
	v_mfma_f32_16x16x32_bf16 v[38:41], v[82:85], v[42:45], v[38:41]
	v_mfma_f32_16x16x32_bf16 v[42:45], v[50:53], v[46:49], 0
	v_mfma_f32_16x16x32_bf16 v[46:49], v[70:73], v[46:49], 0
	v_mfma_f32_16x16x32_bf16 v[42:45], v[62:65], v[54:57], v[42:45]
	v_mfma_f32_16x16x32_bf16 v[46:49], v[82:85], v[54:57], v[46:49]
	v_mfma_f32_16x16x32_bf16 v[54:57], v[50:53], v[58:61], 0
	v_mfma_f32_16x16x32_bf16 v[58:61], v[70:73], v[58:61], 0
	v_mfma_f32_16x16x32_bf16 v[54:57], v[62:65], v[66:69], v[54:57]
	v_mfma_f32_16x16x32_bf16 v[58:61], v[82:85], v[66:69], v[58:61]
	v_mfma_f32_16x16x32_bf16 v[66:69], v[50:53], v[74:77], 0
	v_mfma_f32_16x16x32_bf16 v[74:77], v[70:73], v[74:77], 0
	v_mfma_f32_16x16x32_bf16 v[66:69], v[62:65], v[78:81], v[66:69]
	v_mfma_f32_16x16x32_bf16 v[74:77], v[82:85], v[78:81], v[74:77]
	s_setprio 0
	s_barrier
	ds_read_b128 v[126:129], v244 offset:16384
	ds_read_b128 v[162:165], v244 offset:17408
	ds_read_b128 v[118:121], v244 offset:18432
	ds_read_b128 v[122:125], v244 offset:19456
	ds_read_b128 v[110:113], v244 offset:20480
	ds_read_b128 v[114:117], v244 offset:21504
	ds_read_b128 v[102:105], v244 offset:22528
	ds_read_b128 v[106:109], v244 offset:23552
	s_mov_b32 m0, s10
	s_nop 0
	global_load_lds_dwordx4 v230, s[38:39]
	s_add_u32 m0, m0, 0x2000
	s_nop 0
	global_load_lds_dwordx4 v232, s[38:39]
	s_add_u32 s38, s68, 0x40100
	s_addc_u32 s39, s69, 0
	s_mov_b32 m0, s12
	s_nop 0
	global_load_lds_dwordx4 v230, s[38:39]
	s_add_u32 m0, m0, 0x2000
	s_nop 0
	global_load_lds_dwordx4 v232, s[38:39]
	v_cndmask_b32_e64 v78, 0, 1, s[84:85]
	s_mov_b32 m0, s5
	s_nop 0
	global_load_lds_dwordx4 v0, s[50:51]
	s_add_u32 m0, m0, 0x2000
	s_nop 0
	global_load_lds_dwordx4 v231, s[50:51]
	v_cmp_ne_u32_e64 s[38:39], 1, v78
	s_andn2_b64 vcc, exec, s[84:85]
	s_cbranch_vccnz .LBB0_174
	s_waitcnt vmcnt(8)

; #define PG8_STAGE(bufoff, gbase, voff) glds16s2((voff)[0], (voff)[1], (const void*)(gbase), ldsn + (unsigned)(bufoff))
; #define PG8_LDA(dst, b, h) do { _Pragma("unroll") for (int m = 0; m < 4; ++m) _Pragma("unroll") for (int k = 0; k < 2; ++k) dst[m][k] = *(const LAS bf16x8*)(lds + PG8_SA(b, h) + aoff + m * 2048 + k * 1024); } while (0)
; #define PG8_MMA(ai, bj, At, Bt) do { __builtin_amdgcn_s_setprio(1); _Pragma("unroll") for (int m = 0; m < 4; ++m) _Pragma("unroll") for (int n = 0; n < 2; ++n) _Pragma("unroll") for (int k = 0; k < 2; ++k) \
;         acc[ai][bj][m][n] = __builtin_amdgcn_mfma_f32_16x16x32_bf16(Bt[n][k], At[m][k], acc[ai][bj][m][n], 0, 0, 0); __builtin_amdgcn_s_setprio(0); } while (0)
; #define PG8_WAIT_V(n) asm volatile("s_waitcnt vmcnt(" #n ")" ::: "memory")
; #define PG8_WAIT_L(n) asm volatile("s_waitcnt lgkmcnt(" #n ")" ::: "memory")
; #define PG8_BAR __builtin_amdgcn_s_barrier()
; #define PG8_SCHED __builtin_amdgcn_sched_barrier(0)
; template <class Epi, bool ALIGN_EPI, bool EARLY_DRAIN = true, class Pre = NoPre>
; __device__ __forceinline__ void gemm_phase(LAS unsigned char* lds, const Gemm g, const StaticOrder& S, const Epi& E, int wv, const Pre& pre = Pre()) {
;     ...
;             PG8_WAIT_L(0); PG8_BAR; PG8_MMA(0, 0, At, B0); PG8_MMA(0, 1, At, B1); PG8_BAR; PG8_SCHED;
;             PG8_LDA(At, 1, 1); PG8_STAGE(PG8_SB(1, 0), b3, voffB); PG8_STAGE(PG8_SB(1, 1), b3 + bhs, voffB); PG8_STAGE(PG8_SA(1, 0), a3, voffA);
;             PG8_WAIT_V(8); PG8_WAIT_L(0); PG8_BAR; PG8_MMA(1, 0, At, B0); PG8_MMA(1, 1, At, B1); PG8_BAR; PG8_SCHED;
;         }
.LBB0_177:
	s_add_u32 s36, s84, 0x80
	s_waitcnt lgkmcnt(0)
	s_addc_u32 s37, s85, 0
	s_add_u32 s66, s70, 0x80
	s_addc_u32 s67, s71, 0
	s_barrier
	s_setprio 1
	s_waitcnt lgkmcnt(7)
	v_mfma_f32_16x16x32_bf16 v[122:125], v[146:149], v[186:189], v[122:125]
	v_mfma_f32_16x16x32_bf16 v[114:117], v[154:157], v[186:189], v[114:117]
	s_waitcnt lgkmcnt(5)
	v_mfma_f32_16x16x32_bf16 v[98:101], v[154:157], v[178:181], v[98:101]
	v_mfma_f32_16x16x32_bf16 v[106:109], v[146:149], v[178:181], v[106:109]
	s_waitcnt lgkmcnt(3)
	v_mfma_f32_16x16x32_bf16 v[90:93], v[146:149], v[170:173], v[90:93]
	v_mfma_f32_16x16x32_bf16 v[82:85], v[154:157], v[170:173], v[82:85]
	s_waitcnt lgkmcnt(1)
	v_mfma_f32_16x16x32_bf16 v[50:53], v[154:157], v[162:165], v[50:53]
	v_mfma_f32_16x16x32_bf16 v[62:65], v[146:149], v[162:165], v[62:65]
	v_mfma_f32_16x16x32_bf16 v[122:125], v[150:153], v[190:193], v[122:125]
	v_mfma_f32_16x16x32_bf16 v[114:117], v[158:161], v[190:193], v[114:117]
	v_mfma_f32_16x16x32_bf16 v[98:101], v[158:161], v[182:185], v[98:101]
	v_mfma_f32_16x16x32_bf16 v[106:109], v[150:153], v[182:185], v[106:109]
	v_mfma_f32_16x16x32_bf16 v[90:93], v[150:153], v[174:177], v[90:93]
	v_mfma_f32_16x16x32_bf16 v[82:85], v[158:161], v[174:177], v[82:85]
	s_waitcnt lgkmcnt(0)
	v_mfma_f32_16x16x32_bf16 v[50:53], v[158:161], v[166:169], v[50:53]
	v_mfma_f32_16x16x32_bf16 v[62:65], v[150:153], v[166:169], v[62:65]
	s_setprio 0
	s_setprio 1
	v_mfma_f32_16x16x32_bf16 v[126:129], v[130:133], v[186:189], v[126:129]
	v_mfma_f32_16x16x32_bf16 v[118:121], v[138:141], v[186:189], v[118:121]
	v_mfma_f32_16x16x32_bf16 v[102:105], v[138:141], v[178:181], v[102:105]
	v_mfma_f32_16x16x32_bf16 v[110:113], v[130:133], v[178:181], v[110:113]
	v_mfma_f32_16x16x32_bf16 v[94:97], v[130:133], v[170:173], v[94:97]
	v_mfma_f32_16x16x32_bf16 v[86:89], v[138:141], v[170:173], v[86:89]
	v_mfma_f32_16x16x32_bf16 v[54:57], v[138:141], v[162:165], v[54:57]
	v_mfma_f32_16x16x32_bf16 v[70:73], v[130:133], v[162:165], v[70:73]
	v_mfma_f32_16x16x32_bf16 v[126:129], v[134:137], v[190:193], v[126:129]
	v_mfma_f32_16x16x32_bf16 v[118:121], v[142:145], v[190:193], v[118:121]
	v_mfma_f32_16x16x32_bf16 v[102:105], v[142:145], v[182:185], v[102:105]
	v_mfma_f32_16x16x32_bf16 v[110:113], v[134:137], v[182:185], v[110:113]
	v_mfma_f32_16x16x32_bf16 v[94:97], v[134:137], v[174:177], v[94:97]
	v_mfma_f32_16x16x32_bf16 v[86:89], v[142:145], v[174:177], v[86:89]
	v_mfma_f32_16x16x32_bf16 v[54:57], v[142:145], v[166:169], v[54:57]
	v_mfma_f32_16x16x32_bf16 v[70:73], v[134:137], v[166:169], v[70:73]
	s_setprio 0
	s_barrier
	ds_read_b128 v[162:165], v244 offset:49152
	ds_read_b128 v[166:169], v244 offset:50176
	ds_read_b128 v[170:173], v244 offset:51200
	ds_read_b128 v[174:177], v244 offset:52224
	ds_read_b128 v[178:181], v244 offset:53248
	ds_read_b128 v[182:185], v244 offset:54272
	ds_read_b128 v[186:189], v244 offset:55296
	ds_read_b128 v[190:193], v244 offset:56320
	s_mov_b32 m0, s23
	s_nop 0
	global_load_lds_dwordx4 v230, s[66:67]
	s_add_u32 m0, m0, 0x2000
	s_nop 0
	global_load_lds_dwordx4 v232, s[66:67]
	s_add_u32 s66, s70, 0x40080
	s_addc_u32 s67, s71, 0
	s_mov_b32 m0, s25
	s_nop 0
	global_load_lds_dwordx4 v230, s[66:67]
	s_add_u32 m0, m0, 0x2000
	s_nop 0
	global_load_lds_dwordx4 v232, s[66:67]
	s_nop 0
	s_mov_b32 m0, s24
	s_nop 0
	global_load_lds_dwordx4 v0, s[36:37]
	s_add_u32 m0, m0, 0x2000
	s_nop 0
	global_load_lds_dwordx4 v231, s[36:37]
	s_waitcnt vmcnt(8)
	s_waitcnt lgkmcnt(0)
	s_barrier
	s_setprio 1
	s_waitcnt lgkmcnt(7)
	v_mfma_f32_16x16x32_bf16 v[74:77], v[146:149], v[162:165], v[74:77]
	v_mfma_f32_16x16x32_bf16 v[58:61], v[154:157], v[162:165], v[58:61]
	s_waitcnt lgkmcnt(5)
	v_mfma_f32_16x16x32_bf16 v[34:37], v[154:157], v[170:173], v[34:37]
	v_mfma_f32_16x16x32_bf16 v[42:45], v[146:149], v[170:173], v[42:45]
	s_waitcnt lgkmcnt(3)
	v_mfma_f32_16x16x32_bf16 v[26:29], v[146:149], v[178:181], v[26:29]
	v_mfma_f32_16x16x32_bf16 v[18:21], v[154:157], v[178:181], v[18:21]
	s_waitcnt lgkmcnt(1)
	v_mfma_f32_16x16x32_bf16 v[2:5], v[154:157], v[186:189], v[2:5]
	v_mfma_f32_16x16x32_bf16 v[10:13], v[146:149], v[186:189], v[10:13]
	v_mfma_f32_16x16x32_bf16 v[74:77], v[150:153], v[166:169], v[74:77]
	v_mfma_f32_16x16x32_bf16 v[58:61], v[158:161], v[166:169], v[58:61]
	v_mfma_f32_16x16x32_bf16 v[34:37], v[158:161], v[174:177], v[34:37]
	v_mfma_f32_16x16x32_bf16 v[42:45], v[150:153], v[174:177], v[42:45]
	v_mfma_f32_16x16x32_bf16 v[26:29], v[150:153], v[182:185], v[26:29]
	v_mfma_f32_16x16x32_bf16 v[18:21], v[158:161], v[182:185], v[18:21]
	s_waitcnt lgkmcnt(0)
	v_mfma_f32_16x16x32_bf16 v[2:5], v[158:161], v[190:193], v[2:5]
	v_mfma_f32_16x16x32_bf16 v[10:13], v[150:153], v[190:193], v[10:13]
	s_setprio 0
	s_setprio 1
	v_mfma_f32_16x16x32_bf16 v[78:81], v[130:133], v[162:165], v[78:81]
	v_mfma_f32_16x16x32_bf16 v[66:69], v[138:141], v[162:165], v[66:69]
	v_mfma_f32_16x16x32_bf16 v[38:41], v[138:141], v[170:173], v[38:41]
	v_mfma_f32_16x16x32_bf16 v[46:49], v[130:133], v[170:173], v[46:49]
	v_mfma_f32_16x16x32_bf16 v[30:33], v[130:133], v[178:181], v[30:33]
	v_mfma_f32_16x16x32_bf16 v[22:25], v[138:141], v[178:181], v[22:25]
	v_mfma_f32_16x16x32_bf16 v[6:9], v[138:141], v[186:189], v[6:9]
	v_mfma_f32_16x16x32_bf16 v[14:17], v[130:133], v[186:189], v[14:17]
	v_mfma_f32_16x16x32_bf16 v[78:81], v[134:137], v[166:169], v[78:81]
	v_mfma_f32_16x16x32_bf16 v[66:69], v[142:145], v[166:169], v[66:69]
	v_mfma_f32_16x16x32_bf16 v[38:41], v[142:145], v[174:177], v[38:41]
	v_mfma_f32_16x16x32_bf16 v[46:49], v[134:137], v[174:177], v[46:49]
	v_mfma_f32_16x16x32_bf16 v[30:33], v[134:137], v[182:185], v[30:33]
	v_mfma_f32_16x16x32_bf16 v[22:25], v[142:145], v[182:185], v[22:25]
	v_mfma_f32_16x16x32_bf16 v[6:9], v[142:145], v[190:193], v[6:9]
	v_mfma_f32_16x16x32_bf16 v[14:17], v[134:137], v[190:193], v[14:17]
	s_setprio 0
	s_barrier
	s_add_i32 s64, s64, 2
	s_add_u32 s50, s50, 0x100
	s_addc_u32 s51, s51, 0
	s_add_u32 s52, s52, 0x100
	s_addc_u32 s53, s53, 0
	s_add_u32 s68, s68, 0x100
	s_addc_u32 s69, s69, 0
	s_cmp_gt_u32 s64, 13
	s_cbranch_scc1 .LBB0_184

; #define PG8_STAGE(bufoff, gbase, voff) glds16s2((voff)[0], (voff)[1], (const void*)(gbase), ldsn + (unsigned)(bufoff))
; #define PG8_LDA(dst, b, h) do { _Pragma("unroll") for (int m = 0; m < 4; ++m) _Pragma("unroll") for (int k = 0; k < 2; ++k) dst[m][k] = *(const LAS bf16x8*)(lds + PG8_SA(b, h) + aoff + m * 2048 + k * 1024); } while (0)
; #define PG8_LDB(dst, b, h) do { _Pragma("unroll") for (int n = 0; n < 2; ++n) _Pragma("unroll") for (int k = 0; k < 2; ++k) dst[n][k] = *(const LAS bf16x8*)(lds + PG8_SB(b, h) + boff + n * 2048 + k * 1024); } while (0)
; #define PG8_MMA(ai, bj, At, Bt) do { __builtin_amdgcn_s_setprio(1); _Pragma("unroll") for (int m = 0; m < 4; ++m) _Pragma("unroll") for (int n = 0; n < 2; ++n) _Pragma("unroll") for (int k = 0; k < 2; ++k) \
;         acc[ai][bj][m][n] = __builtin_amdgcn_mfma_f32_16x16x32_bf16(Bt[n][k], At[m][k], acc[ai][bj][m][n], 0, 0, 0); __builtin_amdgcn_s_setprio(0); } while (0)
; template <class Epi, bool ALIGN_EPI, bool EARLY_DRAIN = true, class Pre = NoPre>
; __device__ __forceinline__ void gemm_phase(LAS unsigned char* lds, const Gemm g, const StaticOrder& S, const Epi& E, int wv, const Pre& pre = Pre()) {
;     ...
;             const bool last = (t == nt - 2);
;             const char* a1 = cA + (size_t)(t + 1) * kstep;
;             const char* a2 = last ? nA : cA + (size_t)(t + 2) * kstep; const char* b2 = last ? nB : cB + (size_t)(t + 2) * kstep;
;             const char* a3 = a2 + kstep; const char* b3 = b2 + kstep;
;             int lf_ = EARLY_DRAIN ? __builtin_amdgcn_readfirstlane(landed_flag) : landed_flag; if constexpr (EARLY_DRAIN) asm volatile("" : "+s"(lf_)); landed_flag = 0;
;             PG8_LDB(B0, 0, 0); PG8_LDB(B1, 0, 1); PG8_SCHED; PG8_LDA(At, 0, 0); PG8_STAGE(PG8_SA(1, 1), a1 + ahs, voffA);
;             if (!lf_) PG8_WAIT_V(8);
;             PG8_WAIT_L(0); PG8_BAR; PG8_MMA(0, 0, At, B0); PG8_MMA(0, 1, At, B1); PG8_BAR; PG8_SCHED;
;             PG8_LDA(At, 0, 1); PG8_STAGE(PG8_SB(0, 0), b2, voffB); PG8_STAGE(PG8_SB(0, 1), b2 + bhs, voffB); PG8_STAGE(PG8_SA(0, 0), a2, voffA);
;             if (!lf_) PG8_WAIT_V(8);
;             PG8_WAIT_L(0); PG8_BAR; PG8_MMA(1, 0, At, B0); PG8_MMA(1, 1, At, B1); PG8_BAR; PG8_SCHED;
;             PG8_LDB(B0, 1, 0); PG8_LDB(B1, 1, 1); PG8_SCHED; PG8_LDA(At, 1, 0); PG8_STAGE(PG8_SA(0, 1), a2 + ahs, voffA);
;             if (!lf_) PG8_WAIT_V(8);
.LBB0_180:
	s_waitcnt lgkmcnt(0)
	s_cmp_eq_u32 s64, 12
	s_cselect_b32 s85, s61, s51
	s_cselect_b32 s84, s60, s50
	s_cselect_b32 s71, s43, s53
	s_cselect_b32 s70, s47, s52
	s_barrier
	s_setprio 1
	s_waitcnt lgkmcnt(7)
	v_mfma_f32_16x16x32_bf16 v[122:125], v[146:149], v[186:189], v[122:125]
	v_mfma_f32_16x16x32_bf16 v[114:117], v[154:157], v[186:189], v[114:117]
	s_waitcnt lgkmcnt(5)
	v_mfma_f32_16x16x32_bf16 v[98:101], v[154:157], v[178:181], v[98:101]
	v_mfma_f32_16x16x32_bf16 v[106:109], v[146:149], v[178:181], v[106:109]
	s_waitcnt lgkmcnt(3)
	v_mfma_f32_16x16x32_bf16 v[90:93], v[146:149], v[170:173], v[90:93]
	v_mfma_f32_16x16x32_bf16 v[82:85], v[154:157], v[170:173], v[82:85]
	s_waitcnt lgkmcnt(1)
	v_mfma_f32_16x16x32_bf16 v[50:53], v[154:157], v[162:165], v[50:53]
	v_mfma_f32_16x16x32_bf16 v[62:65], v[146:149], v[162:165], v[62:65]
	v_mfma_f32_16x16x32_bf16 v[122:125], v[150:153], v[190:193], v[122:125]
	v_mfma_f32_16x16x32_bf16 v[114:117], v[158:161], v[190:193], v[114:117]
	v_mfma_f32_16x16x32_bf16 v[98:101], v[158:161], v[182:185], v[98:101]
	v_mfma_f32_16x16x32_bf16 v[106:109], v[150:153], v[182:185], v[106:109]
	v_mfma_f32_16x16x32_bf16 v[90:93], v[150:153], v[174:177], v[90:93]
	v_mfma_f32_16x16x32_bf16 v[82:85], v[158:161], v[174:177], v[82:85]
	s_waitcnt lgkmcnt(0)
	v_mfma_f32_16x16x32_bf16 v[50:53], v[158:161], v[166:169], v[50:53]
	v_mfma_f32_16x16x32_bf16 v[62:65], v[150:153], v[166:169], v[62:65]
	s_setprio 0
	s_setprio 1
	v_mfma_f32_16x16x32_bf16 v[126:129], v[130:133], v[186:189], v[126:129]
	v_mfma_f32_16x16x32_bf16 v[118:121], v[138:141], v[186:189], v[118:121]
	v_mfma_f32_16x16x32_bf16 v[102:105], v[138:141], v[178:181], v[102:105]
	v_mfma_f32_16x16x32_bf16 v[110:113], v[130:133], v[178:181], v[110:113]
	v_mfma_f32_16x16x32_bf16 v[94:97], v[130:133], v[170:173], v[94:97]
	v_mfma_f32_16x16x32_bf16 v[86:89], v[138:141], v[170:173], v[86:89]
	v_mfma_f32_16x16x32_bf16 v[54:57], v[138:141], v[162:165], v[54:57]
	v_mfma_f32_16x16x32_bf16 v[70:73], v[130:133], v[162:165], v[70:73]
	v_mfma_f32_16x16x32_bf16 v[126:129], v[134:137], v[190:193], v[126:129]
	v_mfma_f32_16x16x32_bf16 v[118:121], v[142:145], v[190:193], v[118:121]
	v_mfma_f32_16x16x32_bf16 v[102:105], v[142:145], v[182:185], v[102:105]
	v_mfma_f32_16x16x32_bf16 v[110:113], v[134:137], v[182:185], v[110:113]
	v_mfma_f32_16x16x32_bf16 v[94:97], v[134:137], v[174:177], v[94:97]
	v_mfma_f32_16x16x32_bf16 v[86:89], v[142:145], v[174:177], v[86:89]
	v_mfma_f32_16x16x32_bf16 v[54:57], v[142:145], v[166:169], v[54:57]
	v_mfma_f32_16x16x32_bf16 v[70:73], v[134:137], v[166:169], v[70:73]
	s_setprio 0
	s_barrier
	ds_read_b128 v[186:189], v244 offset:16384
	ds_read_b128 v[190:193], v244 offset:17408
	ds_read_b128 v[178:181], v244 offset:18432
	ds_read_b128 v[182:185], v244 offset:19456
	ds_read_b128 v[170:173], v244 offset:20480
	ds_read_b128 v[174:177], v244 offset:21504
	ds_read_b128 v[162:165], v244 offset:22528
	ds_read_b128 v[166:169], v244 offset:23552
	s_mov_b32 m0, s10
	s_nop 0
	global_load_lds_dwordx4 v230, s[70:71]
	s_add_u32 m0, m0, 0x2000
	s_nop 0
	global_load_lds_dwordx4 v232, s[70:71]
	s_add_u32 s36, s70, 0x40000
	s_addc_u32 s37, s71, 0
	s_mov_b32 m0, s12
	s_nop 0
	global_load_lds_dwordx4 v230, s[36:37]
	s_add_u32 m0, m0, 0x2000
	s_nop 0
	global_load_lds_dwordx4 v232, s[36:37]
	v_cndmask_b32_e64 v194, 0, 1, s[86:87]
	s_mov_b32 m0, s5
	s_nop 0
	global_load_lds_dwordx4 v0, s[84:85]
	s_add_u32 m0, m0, 0x2000
	s_nop 0
	global_load_lds_dwordx4 v231, s[84:85]
	v_cmp_ne_u32_e64 s[36:37], 1, v194
	s_andn2_b64 vcc, exec, s[86:87]
	s_cbranch_vccnz .LBB0_182
	s_waitcnt vmcnt(8)
.LBB0_182:
	s_waitcnt lgkmcnt(0)
	s_barrier
	s_setprio 1
	s_waitcnt lgkmcnt(7)
	v_mfma_f32_16x16x32_bf16 v[74:77], v[146:149], v[186:189], v[74:77]
	v_mfma_f32_16x16x32_bf16 v[58:61], v[154:157], v[186:189], v[58:61]
	s_waitcnt lgkmcnt(5)
	v_mfma_f32_16x16x32_bf16 v[34:37], v[154:157], v[178:181], v[34:37]
	v_mfma_f32_16x16x32_bf16 v[42:45], v[146:149], v[178:181], v[42:45]
	s_waitcnt lgkmcnt(3)
	v_mfma_f32_16x16x32_bf16 v[26:29], v[146:149], v[170:173], v[26:29]
	v_mfma_f32_16x16x32_bf16 v[18:21], v[154:157], v[170:173], v[18:21]
	s_waitcnt lgkmcnt(1)
	v_mfma_f32_16x16x32_bf16 v[2:5], v[154:157], v[162:165], v[2:5]
	v_mfma_f32_16x16x32_bf16 v[10:13], v[146:149], v[162:165], v[10:13]
	v_mfma_f32_16x16x32_bf16 v[74:77], v[150:153], v[190:193], v[74:77]
	v_mfma_f32_16x16x32_bf16 v[58:61], v[158:161], v[190:193], v[58:61]
	v_mfma_f32_16x16x32_bf16 v[34:37], v[158:161], v[182:185], v[34:37]
	v_mfma_f32_16x16x32_bf16 v[42:45], v[150:153], v[182:185], v[42:45]
	v_mfma_f32_16x16x32_bf16 v[26:29], v[150:153], v[174:177], v[26:29]
	v_mfma_f32_16x16x32_bf16 v[18:21], v[158:161], v[174:177], v[18:21]
	s_waitcnt lgkmcnt(0)
	v_mfma_f32_16x16x32_bf16 v[2:5], v[158:161], v[166:169], v[2:5]
	v_mfma_f32_16x16x32_bf16 v[10:13], v[150:153], v[166:169], v[10:13]
	s_setprio 0
	s_setprio 1
	v_mfma_f32_16x16x32_bf16 v[78:81], v[130:133], v[186:189], v[78:81]
	v_mfma_f32_16x16x32_bf16 v[66:69], v[138:141], v[186:189], v[66:69]
	v_mfma_f32_16x16x32_bf16 v[38:41], v[138:141], v[178:181], v[38:41]
	v_mfma_f32_16x16x32_bf16 v[46:49], v[130:133], v[178:181], v[46:49]
	v_mfma_f32_16x16x32_bf16 v[30:33], v[130:133], v[170:173], v[30:33]
	v_mfma_f32_16x16x32_bf16 v[22:25], v[138:141], v[170:173], v[22:25]
	v_mfma_f32_16x16x32_bf16 v[6:9], v[138:141], v[162:165], v[6:9]
	v_mfma_f32_16x16x32_bf16 v[14:17], v[130:133], v[162:165], v[14:17]
	v_mfma_f32_16x16x32_bf16 v[78:81], v[134:137], v[190:193], v[78:81]
	v_mfma_f32_16x16x32_bf16 v[66:69], v[142:145], v[190:193], v[66:69]
	v_mfma_f32_16x16x32_bf16 v[38:41], v[142:145], v[182:185], v[38:41]
	v_mfma_f32_16x16x32_bf16 v[46:49], v[134:137], v[182:185], v[46:49]
	v_mfma_f32_16x16x32_bf16 v[30:33], v[134:137], v[174:177], v[30:33]
	v_mfma_f32_16x16x32_bf16 v[22:25], v[142:145], v[174:177], v[22:25]
	v_mfma_f32_16x16x32_bf16 v[6:9], v[142:145], v[166:169], v[6:9]
	v_mfma_f32_16x16x32_bf16 v[14:17], v[134:137], v[166:169], v[14:17]
	s_setprio 0
	s_barrier
	ds_read_b128 v[146:149], v234
	ds_read_b128 v[150:153], v234 offset:1024
	ds_read_b128 v[154:157], v234 offset:2048
	ds_read_b128 v[158:161], v234 offset:3072
	ds_read_b128 v[130:133], v235
	ds_read_b128 v[134:137], v235 offset:1024
	ds_read_b128 v[138:141], v235 offset:2048
	ds_read_b128 v[142:145], v235 offset:3072
	ds_read_b128 v[186:189], v244 offset:32768
	ds_read_b128 v[190:193], v244 offset:33792
	ds_read_b128 v[178:181], v244 offset:34816
	ds_read_b128 v[182:185], v244 offset:35840
	ds_read_b128 v[170:173], v244 offset:36864
	ds_read_b128 v[174:177], v244 offset:37888
	ds_read_b128 v[162:165], v244 offset:38912
	ds_read_b128 v[166:169], v244 offset:39936
	s_add_u32 s66, s84, 0x40000
	s_addc_u32 s67, s85, 0
	s_mov_b32 m0, s13
	s_nop 0
	global_load_lds_dwordx4 v0, s[66:67]
	s_add_u32 m0, m0, 0x2000
	s_nop 0
	global_load_lds_dwordx4 v231, s[66:67]
	s_and_b64 vcc, exec, s[36:37]
	s_cbranch_vccnz .LBB0_177
	s_waitcnt vmcnt(8)
	s_branch .LBB0_177

; #define PG8_STAGE(bufoff, gbase, voff) glds16s2((voff)[0], (voff)[1], (const void*)(gbase), ldsn + (unsigned)(bufoff))
; #define PG8_LDA(dst, b, h) do { _Pragma("unroll") for (int m = 0; m < 4; ++m) _Pragma("unroll") for (int k = 0; k < 2; ++k) dst[m][k] = *(const LAS bf16x8*)(lds + PG8_SA(b, h) + aoff + m * 2048 + k * 1024); } while (0)
; #define PG8_LDB(dst, b, h) do { _Pragma("unroll") for (int n = 0; n < 2; ++n) _Pragma("unroll") for (int k = 0; k < 2; ++k) dst[n][k] = *(const LAS bf16x8*)(lds + PG8_SB(b, h) + boff + n * 2048 + k * 1024); } while (0)
; #define PG8_MMA(ai, bj, At, Bt) do { __builtin_amdgcn_s_setprio(1); _Pragma("unroll") for (int m = 0; m < 4; ++m) _Pragma("unroll") for (int n = 0; n < 2; ++n) _Pragma("unroll") for (int k = 0; k < 2; ++k) \
;         acc[ai][bj][m][n] = __builtin_amdgcn_mfma_f32_16x16x32_bf16(Bt[n][k], At[m][k], acc[ai][bj][m][n], 0, 0, 0); __builtin_amdgcn_s_setprio(0); } while (0)
; #define PG8_WAIT_V(n) asm volatile("s_waitcnt vmcnt(" #n ")" ::: "memory")
; #define PG8_WAIT_L(n) asm volatile("s_waitcnt lgkmcnt(" #n ")" ::: "memory")
; #define PG8_BAR __builtin_amdgcn_s_barrier()
; template <class Epi, bool ALIGN_EPI, bool EARLY_DRAIN = true, class Pre = NoPre>
; __device__ __forceinline__ void gemm_phase(LAS unsigned char* lds, const Gemm g, const StaticOrder& S, const Epi& E, int wv, const Pre& pre = Pre()) {
;     ...
;             const char* a1 = cA + (size_t)(t + 1) * kstep;
;             const char* a2 = last ? nA : cA + (size_t)(t + 2) * kstep; const char* b2 = last ? nB : cB + (size_t)(t + 2) * kstep;
;             const char* a3 = a2 + kstep; const char* b3 = b2 + kstep;
;             int lf_ = EARLY_DRAIN ? __builtin_amdgcn_readfirstlane(landed_flag) : landed_flag; if constexpr (EARLY_DRAIN) asm volatile("" : "+s"(lf_)); landed_flag = 0;
;             PG8_LDB(B0, 0, 0); PG8_LDB(B1, 0, 1); PG8_SCHED; PG8_LDA(At, 0, 0); PG8_STAGE(PG8_SA(1, 1), a1 + ahs, voffA);
;             if (!lf_) PG8_WAIT_V(8);
;             PG8_WAIT_L(0); PG8_BAR; PG8_MMA(0, 0, At, B0); PG8_MMA(0, 1, At, B1); PG8_BAR; PG8_SCHED;
;             PG8_LDA(At, 0, 1); PG8_STAGE(PG8_SB(0, 0), b2, voffB); PG8_STAGE(PG8_SB(0, 1), b2 + bhs, voffB); PG8_STAGE(PG8_SA(0, 0), a2, voffA);
;             if (!lf_) PG8_WAIT_V(8);
;             PG8_WAIT_L(0); PG8_BAR; PG8_MMA(1, 0, At, B0); PG8_MMA(1, 1, At, B1); PG8_BAR; PG8_SCHED;
.LBB0_442:
	v_add_u32_e32 v0, 0x10000, v203
	ds_read_b128 v[166:169], v0
	ds_read_b128 v[170:173], v0 offset:1024
	ds_read_b128 v[174:177], v0 offset:2048
	ds_read_b128 v[178:181], v0 offset:3072
	v_add_u32_e32 v0, 0x14000, v203
	ds_read_b128 v[182:185], v0
	ds_read_b128 v[186:189], v0 offset:1024
	ds_read_b128 v[190:193], v0 offset:2048
	ds_read_b128 v[194:197], v0 offset:3072
	s_add_i32 s91, s20, 2
	s_cmp_eq_u32 s20, 14
	s_cselect_b32 s86, s45, vcc_lo
	s_cselect_b32 s87, s37, vcc_hi
	s_cselect_b32 s84, s67, s76
	s_cselect_b32 s85, s65, s77
	s_add_u32 s70, s86, 0x80
	s_addc_u32 s71, s87, 0
	ds_read_b128 v[206:209], v204
	ds_read_b128 v[210:213], v204 offset:1024
	ds_read_b128 v[214:217], v204 offset:2048
	ds_read_b128 v[218:221], v204 offset:3072
	ds_read_b128 v[222:225], v204 offset:4096
	ds_read_b128 v[226:229], v204 offset:5120
	ds_read_b128 v[230:233], v204 offset:6144
	ds_read_b128 v[234:237], v204 offset:7168
	s_mov_b32 m0, s26
	s_nop 0
	global_load_lds_dwordx4 v198, s[68:69]
	s_add_u32 m0, m0, 0x2000
	s_nop 0
	global_load_lds_dwordx4 v200, s[68:69]
	s_waitcnt vmcnt(8)
	s_waitcnt lgkmcnt(0)
	s_barrier
	s_setprio 1
	s_waitcnt lgkmcnt(7)
	v_mfma_f32_16x16x32_bf16 v[160:163], v[166:169], v[206:209], v[160:163]
	v_mfma_f32_16x16x32_bf16 v[156:159], v[174:177], v[206:209], v[156:159]
	s_waitcnt lgkmcnt(5)
	v_mfma_f32_16x16x32_bf16 v[140:143], v[174:177], v[214:217], v[140:143]
	v_mfma_f32_16x16x32_bf16 v[144:147], v[166:169], v[214:217], v[144:147]
	s_waitcnt lgkmcnt(3)
	v_mfma_f32_16x16x32_bf16 v[124:127], v[166:169], v[222:225], v[124:127]
	v_mfma_f32_16x16x32_bf16 v[116:119], v[174:177], v[222:225], v[116:119]
	s_waitcnt lgkmcnt(1)
	v_mfma_f32_16x16x32_bf16 v[92:95], v[174:177], v[230:233], v[92:95]
	v_mfma_f32_16x16x32_bf16 v[96:99], v[166:169], v[230:233], v[96:99]
	v_mfma_f32_16x16x32_bf16 v[160:163], v[170:173], v[210:213], v[160:163]
	v_mfma_f32_16x16x32_bf16 v[156:159], v[178:181], v[210:213], v[156:159]
	v_mfma_f32_16x16x32_bf16 v[140:143], v[178:181], v[218:221], v[140:143]
	v_mfma_f32_16x16x32_bf16 v[144:147], v[170:173], v[218:221], v[144:147]
	v_mfma_f32_16x16x32_bf16 v[124:127], v[170:173], v[226:229], v[124:127]
	v_mfma_f32_16x16x32_bf16 v[116:119], v[178:181], v[226:229], v[116:119]
	s_waitcnt lgkmcnt(0)
	v_mfma_f32_16x16x32_bf16 v[92:95], v[178:181], v[234:237], v[92:95]
	v_mfma_f32_16x16x32_bf16 v[96:99], v[170:173], v[234:237], v[96:99]
	s_setprio 0
	s_setprio 1
	v_mfma_f32_16x16x32_bf16 v[152:155], v[182:185], v[206:209], v[152:155]
	v_mfma_f32_16x16x32_bf16 v[148:151], v[190:193], v[206:209], v[148:151]
	v_mfma_f32_16x16x32_bf16 v[132:135], v[190:193], v[214:217], v[132:135]
	v_mfma_f32_16x16x32_bf16 v[136:139], v[182:185], v[214:217], v[136:139]
	v_mfma_f32_16x16x32_bf16 v[112:115], v[182:185], v[222:225], v[112:115]
	v_mfma_f32_16x16x32_bf16 v[108:111], v[190:193], v[222:225], v[108:111]
	v_mfma_f32_16x16x32_bf16 v[80:83], v[190:193], v[230:233], v[80:83]
	v_mfma_f32_16x16x32_bf16 v[88:91], v[182:185], v[230:233], v[88:91]
	v_mfma_f32_16x16x32_bf16 v[152:155], v[186:189], v[210:213], v[152:155]
	v_mfma_f32_16x16x32_bf16 v[148:151], v[194:197], v[210:213], v[148:151]
	v_mfma_f32_16x16x32_bf16 v[132:135], v[194:197], v[218:221], v[132:135]
	v_mfma_f32_16x16x32_bf16 v[136:139], v[186:189], v[218:221], v[136:139]
	v_mfma_f32_16x16x32_bf16 v[112:115], v[186:189], v[226:229], v[112:115]
	v_mfma_f32_16x16x32_bf16 v[108:111], v[194:197], v[226:229], v[108:111]
	v_mfma_f32_16x16x32_bf16 v[80:83], v[194:197], v[234:237], v[80:83]
	v_mfma_f32_16x16x32_bf16 v[88:91], v[186:189], v[234:237], v[88:91]
	s_setprio 0
	s_barrier
	ds_read_b128 v[206:209], v204 offset:16384
	ds_read_b128 v[210:213], v204 offset:17408
	ds_read_b128 v[214:217], v204 offset:18432
	ds_read_b128 v[218:221], v204 offset:19456
	ds_read_b128 v[222:225], v204 offset:20480
	ds_read_b128 v[226:229], v204 offset:21504
	ds_read_b128 v[230:233], v204 offset:22528
	ds_read_b128 v[234:237], v204 offset:23552
	s_mov_b32 m0, s10
	s_nop 0
	global_load_lds_dwordx4 v199, s[84:85]
	s_add_u32 m0, m0, 0x2000
	s_nop 0
	global_load_lds_dwordx4 v201, s[84:85]
	s_add_u32 s14, s84, 0x40000
	s_addc_u32 s15, s85, 0
	s_mov_b32 m0, s12
	s_nop 0
	global_load_lds_dwordx4 v199, s[14:15]
	s_add_u32 m0, m0, 0x2000
	s_nop 0
	global_load_lds_dwordx4 v201, s[14:15]
	s_nop 0
	s_mov_b32 m0, s89
	s_nop 0
	global_load_lds_dwordx4 v198, s[86:87]
	s_add_u32 m0, m0, 0x2000
	s_nop 0
	global_load_lds_dwordx4 v200, s[86:87]
	s_waitcnt vmcnt(8)
	s_waitcnt lgkmcnt(0)
	s_barrier
; #define PG8_STAGE(bufoff, gbase, voff) glds16s2((voff)[0], (voff)[1], (const void*)(gbase), ldsn + (unsigned)(bufoff))
; #define PG8_LDA(dst, b, h) do { _Pragma("unroll") for (int m = 0; m < 4; ++m) _Pragma("unroll") for (int k = 0; k < 2; ++k) dst[m][k] = *(const LAS bf16x8*)(lds + PG8_SA(b, h) + aoff + m * 2048 + k * 1024); } while (0)
; #define PG8_LDB(dst, b, h) do { _Pragma("unroll") for (int n = 0; n < 2; ++n) _Pragma("unroll") for (int k = 0; k < 2; ++k) dst[n][k] = *(const LAS bf16x8*)(lds + PG8_SB(b, h) + boff + n * 2048 + k * 1024); } while (0)
; #define PG8_MMA(ai, bj, At, Bt) do { __builtin_amdgcn_s_setprio(1); _Pragma("unroll") for (int m = 0; m < 4; ++m) _Pragma("unroll") for (int n = 0; n < 2; ++n) _Pragma("unroll") for (int k = 0; k < 2; ++k) \
;         acc[ai][bj][m][n] = __builtin_amdgcn_mfma_f32_16x16x32_bf16(Bt[n][k], At[m][k], acc[ai][bj][m][n], 0, 0, 0); __builtin_amdgcn_s_setprio(0); } while (0)
; #define PG8_WAIT_V(n) asm volatile("s_waitcnt vmcnt(" #n ")" ::: "memory")
; #define PG8_WAIT_L(n) asm volatile("s_waitcnt lgkmcnt(" #n ")" ::: "memory")
; #define PG8_BAR __builtin_amdgcn_s_barrier()
; #define PG8_SCHED __builtin_amdgcn_sched_barrier(0)
; template <class Epi, bool ALIGN_EPI, bool EARLY_DRAIN = true, class Pre = NoPre>
; __device__ __forceinline__ void gemm_phase(LAS unsigned char* lds, const Gemm g, const StaticOrder& S, const Epi& E, int wv, const Pre& pre = Pre()) {
;     ...
;             PG8_WAIT_L(0); PG8_BAR; PG8_MMA(1, 0, At, B0); PG8_MMA(1, 1, At, B1); PG8_BAR; PG8_SCHED;
;             PG8_LDB(B0, 1, 0); PG8_LDB(B1, 1, 1); PG8_SCHED; PG8_LDA(At, 1, 0); PG8_STAGE(PG8_SA(0, 1), a2 + ahs, voffA);
;             if (!lf_) PG8_WAIT_V(8);
;             PG8_WAIT_L(0); PG8_BAR; PG8_MMA(0, 0, At, B0); PG8_MMA(0, 1, At, B1); PG8_BAR; PG8_SCHED;
	s_setprio 1
	s_waitcnt lgkmcnt(7)
	v_mfma_f32_16x16x32_bf16 v[72:75], v[166:169], v[206:209], v[72:75]
	v_mfma_f32_16x16x32_bf16 v[68:71], v[174:177], v[206:209], v[68:71]
	s_waitcnt lgkmcnt(5)
	v_mfma_f32_16x16x32_bf16 v[44:47], v[174:177], v[214:217], v[44:47]
	v_mfma_f32_16x16x32_bf16 v[48:51], v[166:169], v[214:217], v[48:51]
	s_waitcnt lgkmcnt(3)
	v_mfma_f32_16x16x32_bf16 v[32:35], v[166:169], v[222:225], v[32:35]
	v_mfma_f32_16x16x32_bf16 v[28:31], v[174:177], v[222:225], v[28:31]
	s_waitcnt lgkmcnt(1)
	v_mfma_f32_16x16x32_bf16 v[12:15], v[174:177], v[230:233], v[12:15]
	v_mfma_f32_16x16x32_bf16 v[16:19], v[166:169], v[230:233], v[16:19]
	v_mfma_f32_16x16x32_bf16 v[72:75], v[170:173], v[210:213], v[72:75]
	v_mfma_f32_16x16x32_bf16 v[68:71], v[178:181], v[210:213], v[68:71]
	v_mfma_f32_16x16x32_bf16 v[44:47], v[178:181], v[218:221], v[44:47]
	v_mfma_f32_16x16x32_bf16 v[48:51], v[170:173], v[218:221], v[48:51]
	v_mfma_f32_16x16x32_bf16 v[32:35], v[170:173], v[226:229], v[32:35]
	v_mfma_f32_16x16x32_bf16 v[28:31], v[178:181], v[226:229], v[28:31]
	s_waitcnt lgkmcnt(0)
	v_mfma_f32_16x16x32_bf16 v[12:15], v[178:181], v[234:237], v[12:15]
	v_mfma_f32_16x16x32_bf16 v[16:19], v[170:173], v[234:237], v[16:19]
	s_setprio 0
	s_setprio 1
	v_mfma_f32_16x16x32_bf16 v[60:63], v[182:185], v[206:209], v[60:63]
	v_mfma_f32_16x16x32_bf16 v[56:59], v[190:193], v[206:209], v[56:59]
	v_mfma_f32_16x16x32_bf16 v[36:39], v[190:193], v[214:217], v[36:39]
	v_mfma_f32_16x16x32_bf16 v[40:43], v[182:185], v[214:217], v[40:43]
	v_mfma_f32_16x16x32_bf16 v[24:27], v[182:185], v[222:225], v[24:27]
	v_mfma_f32_16x16x32_bf16 v[20:23], v[190:193], v[222:225], v[20:23]
	v_mfma_f32_16x16x32_bf16 v[2:5], v[190:193], v[230:233], v[4:7]
	v_mfma_f32_16x16x32_bf16 v[8:11], v[182:185], v[230:233], v[8:11]
	v_mfma_f32_16x16x32_bf16 v[60:63], v[186:189], v[210:213], v[60:63]
	v_mfma_f32_16x16x32_bf16 v[56:59], v[194:197], v[210:213], v[56:59]
	v_mfma_f32_16x16x32_bf16 v[36:39], v[194:197], v[218:221], v[36:39]
	v_mfma_f32_16x16x32_bf16 v[40:43], v[186:189], v[218:221], v[40:43]
	v_mfma_f32_16x16x32_bf16 v[24:27], v[186:189], v[226:229], v[24:27]
	v_mfma_f32_16x16x32_bf16 v[20:23], v[194:197], v[226:229], v[20:23]
	v_mfma_f32_16x16x32_bf16 v[2:5], v[194:197], v[234:237], v[2:5]
	v_mfma_f32_16x16x32_bf16 v[8:11], v[186:189], v[234:237], v[8:11]
	s_setprio 0
	s_barrier
	v_add_u32_e32 v0, 0x18000, v203
	ds_read_b128 v[166:169], v0
	ds_read_b128 v[170:173], v0 offset:1024
	ds_read_b128 v[174:177], v0 offset:2048
	ds_read_b128 v[178:181], v0 offset:3072
	v_add_u32_e32 v0, 0x1c000, v203
	ds_read_b128 v[182:185], v0
	ds_read_b128 v[186:189], v0 offset:1024
	ds_read_b128 v[190:193], v0 offset:2048
	ds_read_b128 v[194:197], v0 offset:3072
	ds_read_b128 v[206:209], v204 offset:32768
	ds_read_b128 v[210:213], v204 offset:33792
	ds_read_b128 v[214:217], v204 offset:34816
	ds_read_b128 v[218:221], v204 offset:35840
	ds_read_b128 v[222:225], v204 offset:36864
	ds_read_b128 v[226:229], v204 offset:37888
	ds_read_b128 v[230:233], v204 offset:38912
	ds_read_b128 v[234:237], v204 offset:39936
	s_add_u32 s14, s86, 0x40000
	s_addc_u32 s15, s87, 0
	s_mov_b32 m0, s13
	s_nop 0
	global_load_lds_dwordx4 v198, s[14:15]
	s_add_u32 m0, m0, 0x2000
	s_nop 0
	global_load_lds_dwordx4 v200, s[14:15]
	s_waitcnt vmcnt(8)
	s_waitcnt lgkmcnt(0)
	s_barrier
	s_setprio 1
	s_waitcnt lgkmcnt(7)
	v_mfma_f32_16x16x32_bf16 v[160:163], v[166:169], v[206:209], v[160:163]
	v_mfma_f32_16x16x32_bf16 v[156:159], v[174:177], v[206:209], v[156:159]
	s_waitcnt lgkmcnt(5)
	v_mfma_f32_16x16x32_bf16 v[140:143], v[174:177], v[214:217], v[140:143]
	v_mfma_f32_16x16x32_bf16 v[144:147], v[166:169], v[214:217], v[144:147]
	s_waitcnt lgkmcnt(3)
	v_mfma_f32_16x16x32_bf16 v[124:127], v[166:169], v[222:225], v[124:127]
	v_mfma_f32_16x16x32_bf16 v[116:119], v[174:177], v[222:225], v[116:119]
	s_waitcnt lgkmcnt(1)
	v_mfma_f32_16x16x32_bf16 v[92:95], v[174:177], v[230:233], v[92:95]
	v_mfma_f32_16x16x32_bf16 v[96:99], v[166:169], v[230:233], v[96:99]
	v_mfma_f32_16x16x32_bf16 v[160:163], v[170:173], v[210:213], v[160:163]
	v_mfma_f32_16x16x32_bf16 v[156:159], v[178:181], v[210:213], v[156:159]
	v_mfma_f32_16x16x32_bf16 v[140:143], v[178:181], v[218:221], v[140:143]
	v_mfma_f32_16x16x32_bf16 v[144:147], v[170:173], v[218:221], v[144:147]
	v_mfma_f32_16x16x32_bf16 v[124:127], v[170:173], v[226:229], v[124:127]
	v_mfma_f32_16x16x32_bf16 v[116:119], v[178:181], v[226:229], v[116:119]
	s_waitcnt lgkmcnt(0)
	v_mfma_f32_16x16x32_bf16 v[92:95], v[178:181], v[234:237], v[92:95]
	v_mfma_f32_16x16x32_bf16 v[96:99], v[170:173], v[234:237], v[96:99]
	s_setprio 0
	s_setprio 1
	v_mfma_f32_16x16x32_bf16 v[152:155], v[182:185], v[206:209], v[152:155]
	v_mfma_f32_16x16x32_bf16 v[148:151], v[190:193], v[206:209], v[148:151]
	v_mfma_f32_16x16x32_bf16 v[132:135], v[190:193], v[214:217], v[132:135]
	v_mfma_f32_16x16x32_bf16 v[136:139], v[182:185], v[214:217], v[136:139]
	v_mfma_f32_16x16x32_bf16 v[112:115], v[182:185], v[222:225], v[112:115]
	v_mfma_f32_16x16x32_bf16 v[108:111], v[190:193], v[222:225], v[108:111]
	v_mfma_f32_16x16x32_bf16 v[80:83], v[190:193], v[230:233], v[80:83]
	v_mfma_f32_16x16x32_bf16 v[88:91], v[182:185], v[230:233], v[88:91]
	v_mfma_f32_16x16x32_bf16 v[152:155], v[186:189], v[210:213], v[152:155]
	v_mfma_f32_16x16x32_bf16 v[148:151], v[194:197], v[210:213], v[148:151]
	v_mfma_f32_16x16x32_bf16 v[132:135], v[194:197], v[218:221], v[132:135]
	v_mfma_f32_16x16x32_bf16 v[136:139], v[186:189], v[218:221], v[136:139]
	v_mfma_f32_16x16x32_bf16 v[112:115], v[186:189], v[226:229], v[112:115]
	v_mfma_f32_16x16x32_bf16 v[108:111], v[194:197], v[226:229], v[108:111]
	v_mfma_f32_16x16x32_bf16 v[80:83], v[194:197], v[234:237], v[80:83]
	v_mfma_f32_16x16x32_bf16 v[88:91], v[186:189], v[234:237], v[88:91]
	s_setprio 0
	s_barrier
; #define PG8_STAGE(bufoff, gbase, voff) glds16s2((voff)[0], (voff)[1], (const void*)(gbase), ldsn + (unsigned)(bufoff))
; #define PG8_LDA(dst, b, h) do { _Pragma("unroll") for (int m = 0; m < 4; ++m) _Pragma("unroll") for (int k = 0; k < 2; ++k) dst[m][k] = *(const LAS bf16x8*)(lds + PG8_SA(b, h) + aoff + m * 2048 + k * 1024); } while (0)
; #define PG8_MMA(ai, bj, At, Bt) do { __builtin_amdgcn_s_setprio(1); _Pragma("unroll") for (int m = 0; m < 4; ++m) _Pragma("unroll") for (int n = 0; n < 2; ++n) _Pragma("unroll") for (int k = 0; k < 2; ++k) \
;         acc[ai][bj][m][n] = __builtin_amdgcn_mfma_f32_16x16x32_bf16(Bt[n][k], At[m][k], acc[ai][bj][m][n], 0, 0, 0); __builtin_amdgcn_s_setprio(0); } while (0)
; #define PG8_WAIT_V(n) asm volatile("s_waitcnt vmcnt(" #n ")" ::: "memory")
; #define PG8_WAIT_L(n) asm volatile("s_waitcnt lgkmcnt(" #n ")" ::: "memory")
; #define PG8_BAR __builtin_amdgcn_s_barrier()
; #define PG8_SCHED __builtin_amdgcn_sched_barrier(0)
; template <class Epi, bool ALIGN_EPI, bool EARLY_DRAIN = true, class Pre = NoPre>
; __device__ __forceinline__ void gemm_phase(LAS unsigned char* lds, const Gemm g, const StaticOrder& S, const Epi& E, int wv, const Pre& pre = Pre()) {
;     ...
;             PG8_LDA(At, 1, 1); PG8_STAGE(PG8_SB(1, 0), b3, voffB); PG8_STAGE(PG8_SB(1, 1), b3 + bhs, voffB); PG8_STAGE(PG8_SA(1, 0), a3, voffA);
;             PG8_WAIT_V(8); PG8_WAIT_L(0); PG8_BAR; PG8_MMA(1, 0, At, B0); PG8_MMA(1, 1, At, B1); PG8_BAR; PG8_SCHED;
;         }
;         }
;         if constexpr (ALIGN_EPI) { if (wr == 0) PG8_BAR; }
	ds_read_b128 v[206:209], v204 offset:49152
	ds_read_b128 v[210:213], v204 offset:50176
	ds_read_b128 v[214:217], v204 offset:51200
	ds_read_b128 v[218:221], v204 offset:52224
	ds_read_b128 v[222:225], v204 offset:53248
	ds_read_b128 v[226:229], v204 offset:54272
	ds_read_b128 v[230:233], v204 offset:55296
	ds_read_b128 v[234:237], v204 offset:56320
	s_add_u32 s14, s84, 0x80
	s_addc_u32 s15, s85, 0
	s_mov_b32 m0, s23
	s_nop 0
	global_load_lds_dwordx4 v199, s[14:15]
	s_add_u32 m0, m0, 0x2000
	s_nop 0
	global_load_lds_dwordx4 v201, s[14:15]
	s_add_u32 s14, s84, 0x40080
	s_addc_u32 s15, s85, 0
	s_mov_b32 m0, s25
	s_nop 0
	global_load_lds_dwordx4 v199, s[14:15]
	s_add_u32 m0, m0, 0x2000
	s_nop 0
	global_load_lds_dwordx4 v201, s[14:15]
	s_nop 0
	s_mov_b32 m0, s24
	s_nop 0
	global_load_lds_dwordx4 v198, s[70:71]
	s_add_u32 m0, m0, 0x2000
	s_nop 0
	global_load_lds_dwordx4 v200, s[70:71]
	s_waitcnt vmcnt(8)
	s_waitcnt lgkmcnt(0)
	s_barrier
	s_setprio 1
	s_waitcnt lgkmcnt(7)
	v_mfma_f32_16x16x32_bf16 v[72:75], v[166:169], v[206:209], v[72:75]
	v_mfma_f32_16x16x32_bf16 v[68:71], v[174:177], v[206:209], v[68:71]
	s_waitcnt lgkmcnt(5)
	v_mfma_f32_16x16x32_bf16 v[44:47], v[174:177], v[214:217], v[44:47]
	v_mfma_f32_16x16x32_bf16 v[48:51], v[166:169], v[214:217], v[48:51]
	s_waitcnt lgkmcnt(3)
	v_mfma_f32_16x16x32_bf16 v[32:35], v[166:169], v[222:225], v[32:35]
	v_mfma_f32_16x16x32_bf16 v[28:31], v[174:177], v[222:225], v[28:31]
	s_waitcnt lgkmcnt(1)
	v_mfma_f32_16x16x32_bf16 v[12:15], v[174:177], v[230:233], v[12:15]
	v_mfma_f32_16x16x32_bf16 v[16:19], v[166:169], v[230:233], v[16:19]
	v_mfma_f32_16x16x32_bf16 v[72:75], v[170:173], v[210:213], v[72:75]
	v_mfma_f32_16x16x32_bf16 v[68:71], v[178:181], v[210:213], v[68:71]
	v_mfma_f32_16x16x32_bf16 v[44:47], v[178:181], v[218:221], v[44:47]
	v_mfma_f32_16x16x32_bf16 v[48:51], v[170:173], v[218:221], v[48:51]
	v_mfma_f32_16x16x32_bf16 v[32:35], v[170:173], v[226:229], v[32:35]
	v_mfma_f32_16x16x32_bf16 v[28:31], v[178:181], v[226:229], v[28:31]
	s_waitcnt lgkmcnt(0)
	v_mfma_f32_16x16x32_bf16 v[12:15], v[178:181], v[234:237], v[12:15]
	v_mfma_f32_16x16x32_bf16 v[16:19], v[170:173], v[234:237], v[16:19]
	s_setprio 0
	s_setprio 1
	v_mfma_f32_16x16x32_bf16 v[60:63], v[182:185], v[206:209], v[60:63]
	v_mfma_f32_16x16x32_bf16 v[56:59], v[190:193], v[206:209], v[56:59]
	v_mfma_f32_16x16x32_bf16 v[36:39], v[190:193], v[214:217], v[36:39]
	v_mfma_f32_16x16x32_bf16 v[40:43], v[182:185], v[214:217], v[40:43]
	v_mfma_f32_16x16x32_bf16 v[24:27], v[182:185], v[222:225], v[24:27]
	v_mfma_f32_16x16x32_bf16 v[20:23], v[190:193], v[222:225], v[20:23]
	v_mfma_f32_16x16x32_bf16 v[2:5], v[190:193], v[230:233], v[2:5]
	v_mfma_f32_16x16x32_bf16 v[6:9], v[182:185], v[230:233], v[8:11]
	v_mfma_f32_16x16x32_bf16 v[60:63], v[186:189], v[210:213], v[60:63]
	v_mfma_f32_16x16x32_bf16 v[56:59], v[194:197], v[210:213], v[56:59]
	v_mfma_f32_16x16x32_bf16 v[36:39], v[194:197], v[218:221], v[36:39]
	v_mfma_f32_16x16x32_bf16 v[40:43], v[186:189], v[218:221], v[40:43]
	v_mfma_f32_16x16x32_bf16 v[24:27], v[186:189], v[226:229], v[24:27]
	v_mfma_f32_16x16x32_bf16 v[20:23], v[194:197], v[226:229], v[20:23]
	v_mfma_f32_16x16x32_bf16 v[8:11], v[186:189], v[234:237], v[6:9]
	v_mfma_f32_16x16x32_bf16 v[4:7], v[194:197], v[234:237], v[2:5]
	s_setprio 0
	s_barrier
	s_add_u32 s68, s68, 0x100
	s_addc_u32 s69, s69, 0
	s_add_u32 vcc_lo, vcc_lo, 0x100
	s_addc_u32 vcc_hi, vcc_hi, 0
	s_add_u32 s76, s76, 0x100
	s_addc_u32 s77, s77, 0
	s_cmp_ge_u32 s91, s0
	s_mov_b32 s20, s91
	s_cbranch_scc0 .LBB0_442
	s_mov_b32 s20, 8
	s_andn2_b64 vcc, exec, s[60:61]
	s_mov_b64 s[60:61], 0
	s_cbranch_vccnz .LBB0_439
	s_and_b64 vcc, exec, s[18:19]
	s_cbranch_vccz .LBB0_446
	s_barrier

; #define PG8_STAGE(bufoff, gbase, voff) glds16s2((voff)[0], (voff)[1], (const void*)(gbase), ldsn + (unsigned)(bufoff))
; #define PG8_LDA(dst, b, h) do { _Pragma("unroll") for (int m = 0; m < 4; ++m) _Pragma("unroll") for (int k = 0; k < 2; ++k) dst[m][k] = *(const LAS bf16x8*)(lds + PG8_SA(b, h) + aoff + m * 2048 + k * 1024); } while (0)
; #define PG8_LDB(dst, b, h) do { _Pragma("unroll") for (int n = 0; n < 2; ++n) _Pragma("unroll") for (int k = 0; k < 2; ++k) dst[n][k] = *(const LAS bf16x8*)(lds + PG8_SB(b, h) + boff + n * 2048 + k * 1024); } while (0)
; #define PG8_MMA(ai, bj, At, Bt) do { __builtin_amdgcn_s_setprio(1); _Pragma("unroll") for (int m = 0; m < 4; ++m) _Pragma("unroll") for (int n = 0; n < 2; ++n) _Pragma("unroll") for (int k = 0; k < 2; ++k) \
;         acc[ai][bj][m][n] = __builtin_amdgcn_mfma_f32_16x16x32_bf16(Bt[n][k], At[m][k], acc[ai][bj][m][n], 0, 0, 0); __builtin_amdgcn_s_setprio(0); } while (0)
; #define PG8_WAIT_V(n) asm volatile("s_waitcnt vmcnt(" #n ")" ::: "memory")
; #define PG8_WAIT_L(n) asm volatile("s_waitcnt lgkmcnt(" #n ")" ::: "memory")
; #define PG8_BAR __builtin_amdgcn_s_barrier()
; #define PG8_SCHED __builtin_amdgcn_sched_barrier(0)
; template <class Epi, bool ALIGN_EPI, bool EARLY_DRAIN = true, class Pre = NoPre>
; __device__ __forceinline__ void gemm_phase(LAS unsigned char* lds, const Gemm g, const StaticOrder& S, const Epi& E, int wv, const Pre& pre = Pre()) {
;     ...
;             PG8_LDB(B0, 0, 0); PG8_LDB(B1, 0, 1); PG8_SCHED; PG8_LDA(At, 0, 0); PG8_STAGE(PG8_SA(1, 1), a1 + ahs, voffA);
;             if (!lf_) PG8_WAIT_V(8);
;             PG8_WAIT_L(0); PG8_BAR; PG8_MMA(0, 0, At, B0); PG8_MMA(0, 1, At, B1); PG8_BAR; PG8_SCHED;
;             PG8_LDA(At, 0, 1); PG8_STAGE(PG8_SB(0, 0), b2, voffB); PG8_STAGE(PG8_SB(0, 1), b2 + bhs, voffB); PG8_STAGE(PG8_SA(0, 0), a2, voffA);
;             if (!lf_) PG8_WAIT_V(8);
.LBB0_553:
	s_add_u32 s14, s86, 0x100
	s_addc_u32 s15, s87, 0
	s_waitcnt lgkmcnt(0)
	s_add_u32 s42, s84, 0x100
	s_addc_u32 s43, s85, 0
	s_barrier
	s_setprio 1
	s_waitcnt lgkmcnt(7)
	v_mfma_f32_16x16x32_bf16 v[2:5], v[74:77], v[38:41], 0
	v_mfma_f32_16x16x32_bf16 v[6:9], v[86:89], v[38:41], 0
	s_waitcnt lgkmcnt(5)
	v_mfma_f32_16x16x32_bf16 v[10:13], v[74:77], v[46:49], 0
	v_mfma_f32_16x16x32_bf16 v[14:17], v[86:89], v[46:49], 0
	s_waitcnt lgkmcnt(3)
	v_mfma_f32_16x16x32_bf16 v[18:21], v[74:77], v[62:65], 0
	v_mfma_f32_16x16x32_bf16 v[22:25], v[86:89], v[62:65], 0
	s_waitcnt lgkmcnt(1)
	v_mfma_f32_16x16x32_bf16 v[26:29], v[74:77], v[90:93], 0
	v_mfma_f32_16x16x32_bf16 v[30:33], v[86:89], v[90:93], 0
	v_mfma_f32_16x16x32_bf16 v[2:5], v[82:85], v[42:45], v[2:5]
	v_mfma_f32_16x16x32_bf16 v[6:9], v[96:99], v[42:45], v[6:9]
	v_mfma_f32_16x16x32_bf16 v[14:17], v[96:99], v[58:61], v[14:17]
	v_mfma_f32_16x16x32_bf16 v[10:13], v[82:85], v[58:61], v[10:13]
	v_mfma_f32_16x16x32_bf16 v[18:21], v[82:85], v[78:81], v[18:21]
	v_mfma_f32_16x16x32_bf16 v[22:25], v[96:99], v[78:81], v[22:25]
	s_waitcnt lgkmcnt(0)
	v_mfma_f32_16x16x32_bf16 v[30:33], v[96:99], v[100:103], v[30:33]
	v_mfma_f32_16x16x32_bf16 v[26:29], v[82:85], v[100:103], v[26:29]
	s_setprio 0
	s_setprio 1
	v_mfma_f32_16x16x32_bf16 v[34:37], v[50:53], v[38:41], 0
	v_mfma_f32_16x16x32_bf16 v[38:41], v[66:69], v[38:41], 0
	v_mfma_f32_16x16x32_bf16 v[34:37], v[54:57], v[42:45], v[34:37]
	v_mfma_f32_16x16x32_bf16 v[38:41], v[70:73], v[42:45], v[38:41]
	v_mfma_f32_16x16x32_bf16 v[42:45], v[50:53], v[46:49], 0
	v_mfma_f32_16x16x32_bf16 v[46:49], v[66:69], v[46:49], 0
	v_mfma_f32_16x16x32_bf16 v[42:45], v[54:57], v[58:61], v[42:45]
	v_mfma_f32_16x16x32_bf16 v[46:49], v[70:73], v[58:61], v[46:49]
	v_mfma_f32_16x16x32_bf16 v[58:61], v[50:53], v[62:65], 0
	v_mfma_f32_16x16x32_bf16 v[62:65], v[66:69], v[62:65], 0
	v_mfma_f32_16x16x32_bf16 v[58:61], v[54:57], v[78:81], v[58:61]
	v_mfma_f32_16x16x32_bf16 v[62:65], v[70:73], v[78:81], v[62:65]
	v_mfma_f32_16x16x32_bf16 v[78:81], v[50:53], v[90:93], 0
	v_mfma_f32_16x16x32_bf16 v[90:93], v[66:69], v[90:93], 0
	v_mfma_f32_16x16x32_bf16 v[78:81], v[54:57], v[100:103], v[78:81]
	v_mfma_f32_16x16x32_bf16 v[92:95], v[70:73], v[100:103], v[90:93]
	s_setprio 0
	s_barrier
	ds_read_b128 v[162:165], v245 offset:16384
	ds_read_b128 v[166:169], v245 offset:17408
	ds_read_b128 v[154:157], v245 offset:18432
	ds_read_b128 v[158:161], v245 offset:19456
	ds_read_b128 v[146:149], v245 offset:20480
	ds_read_b128 v[150:153], v245 offset:21504
	ds_read_b128 v[110:113], v245 offset:22528
	ds_read_b128 v[126:129], v245 offset:23552
	s_mov_b32 m0, s22
	s_nop 0
	global_load_lds_dwordx4 v251, s[42:43]
	s_add_u32 m0, m0, 0x2000
	s_nop 0
	global_load_lds_dwordx4 v247, s[42:43]
	s_add_u32 s42, s84, 0x580100
	s_addc_u32 s43, s85, 0
	s_mov_b32 m0, s23
	s_nop 0
	global_load_lds_dwordx4 v251, s[42:43]
	s_add_u32 m0, m0, 0x2000
	s_nop 0
	global_load_lds_dwordx4 v247, s[42:43]
	v_cndmask_b32_e64 v90, 0, 1, s[88:89]
	s_mov_b32 m0, s13
	s_nop 0
	global_load_lds_dwordx4 v250, s[14:15]
	s_add_u32 m0, m0, 0x2000
	s_nop 0
	global_load_lds_dwordx4 v246, s[14:15]
	v_cmp_ne_u32_e64 s[42:43], 1, v90
	s_andn2_b64 vcc, exec, s[88:89]
	s_cbranch_vccnz .LBB0_555
	s_waitcnt vmcnt(8)

; #define PG8_STAGE(bufoff, gbase, voff) glds16s2((voff)[0], (voff)[1], (const void*)(gbase), ldsn + (unsigned)(bufoff))
; #define PG8_LDA(dst, b, h) do { _Pragma("unroll") for (int m = 0; m < 4; ++m) _Pragma("unroll") for (int k = 0; k < 2; ++k) dst[m][k] = *(const LAS bf16x8*)(lds + PG8_SA(b, h) + aoff + m * 2048 + k * 1024); } while (0)
; #define PG8_MMA(ai, bj, At, Bt) do { __builtin_amdgcn_s_setprio(1); _Pragma("unroll") for (int m = 0; m < 4; ++m) _Pragma("unroll") for (int n = 0; n < 2; ++n) _Pragma("unroll") for (int k = 0; k < 2; ++k) \
;         acc[ai][bj][m][n] = __builtin_amdgcn_mfma_f32_16x16x32_bf16(Bt[n][k], At[m][k], acc[ai][bj][m][n], 0, 0, 0); __builtin_amdgcn_s_setprio(0); } while (0)
; #define PG8_WAIT_V(n) asm volatile("s_waitcnt vmcnt(" #n ")" ::: "memory")
; #define PG8_WAIT_L(n) asm volatile("s_waitcnt lgkmcnt(" #n ")" ::: "memory")
; #define PG8_BAR __builtin_amdgcn_s_barrier()
; #define PG8_SCHED __builtin_amdgcn_sched_barrier(0)
; template <class Epi, bool ALIGN_EPI, bool EARLY_DRAIN = true, class Pre = NoPre>
; __device__ __forceinline__ void gemm_phase(LAS unsigned char* lds, const Gemm g, const StaticOrder& S, const Epi& E, int wv, const Pre& pre = Pre()) {
;     ...
;             PG8_WAIT_L(0); PG8_BAR; PG8_MMA(0, 0, At, B0); PG8_MMA(0, 1, At, B1); PG8_BAR; PG8_SCHED;
;             PG8_LDA(At, 1, 1); PG8_STAGE(PG8_SB(1, 0), b3, voffB); PG8_STAGE(PG8_SB(1, 1), b3 + bhs, voffB); PG8_STAGE(PG8_SA(1, 0), a3, voffA);
;             PG8_WAIT_V(8); PG8_WAIT_L(0); PG8_BAR; PG8_MMA(1, 0, At, B0); PG8_MMA(1, 1, At, B1); PG8_BAR; PG8_SCHED;
;         }
.LBB0_558:
	s_add_u32 s14, s86, 0x80
	s_waitcnt lgkmcnt(0)
	s_addc_u32 s15, s87, 0
	s_add_u32 s40, s84, 0x80
	s_addc_u32 s41, s85, 0
	s_barrier
	s_setprio 1
	s_waitcnt lgkmcnt(7)
	v_mfma_f32_16x16x32_bf16 v[78:81], v[178:181], v[154:157], v[78:81]
	s_waitcnt lgkmcnt(6)
	v_mfma_f32_16x16x32_bf16 v[146:149], v[182:185], v[202:205], v[78:81]
	s_waitcnt lgkmcnt(5)
	v_mfma_f32_16x16x32_bf16 v[78:81], v[178:181], v[126:129], v[92:95]
	v_mfma_f32_16x16x32_bf16 v[70:73], v[162:165], v[154:157], v[70:73]
	v_mfma_f32_16x16x32_bf16 v[74:77], v[162:165], v[126:129], v[74:77]
	s_waitcnt lgkmcnt(4)
	v_mfma_f32_16x16x32_bf16 v[150:153], v[182:185], v[158:161], v[78:81]
	s_waitcnt lgkmcnt(3)
	v_mfma_f32_16x16x32_bf16 v[78:81], v[162:165], v[194:197], v[82:85]
	v_mfma_f32_16x16x32_bf16 v[66:69], v[178:181], v[194:197], v[66:69]
	s_waitcnt lgkmcnt(1)
	v_mfma_f32_16x16x32_bf16 v[50:53], v[178:181], v[186:189], v[50:53]
	v_mfma_f32_16x16x32_bf16 v[54:57], v[162:165], v[186:189], v[54:57]
	v_mfma_f32_16x16x32_bf16 v[70:73], v[174:177], v[202:205], v[70:73]
	v_mfma_f32_16x16x32_bf16 v[74:77], v[174:177], v[158:161], v[74:77]
	v_mfma_f32_16x16x32_bf16 v[82:85], v[174:177], v[198:201], v[78:81]
	v_mfma_f32_16x16x32_bf16 v[66:69], v[182:185], v[198:201], v[66:69]
	s_waitcnt lgkmcnt(0)
	v_mfma_f32_16x16x32_bf16 v[50:53], v[182:185], v[190:193], v[50:53]
	v_mfma_f32_16x16x32_bf16 v[54:57], v[174:177], v[190:193], v[54:57]
	s_setprio 0
	s_setprio 1
	v_mfma_f32_16x16x32_bf16 v[78:81], v[138:141], v[154:157], v[86:89]
	v_mfma_f32_16x16x32_bf16 v[88:91], v[142:145], v[202:205], v[78:81]
	v_mfma_f32_16x16x32_bf16 v[78:81], v[166:169], v[154:157], v[102:105]
	v_mfma_f32_16x16x32_bf16 v[154:157], v[170:173], v[202:205], v[78:81]
	v_mfma_f32_16x16x32_bf16 v[78:81], v[138:141], v[126:129], v[96:99]
	v_mfma_f32_16x16x32_bf16 v[98:101], v[142:145], v[158:161], v[78:81]
	v_mfma_f32_16x16x32_bf16 v[78:81], v[166:169], v[126:129], v[118:121]
	v_mfma_f32_16x16x32_bf16 v[158:161], v[170:173], v[158:161], v[78:81]
	v_mfma_f32_16x16x32_bf16 v[78:81], v[138:141], v[194:197], v[122:125]
	v_mfma_f32_16x16x32_bf16 v[126:129], v[142:145], v[198:201], v[78:81]
	v_mfma_f32_16x16x32_bf16 v[78:81], v[166:169], v[194:197], v[110:113]
	v_mfma_f32_16x16x32_bf16 v[62:65], v[138:141], v[186:189], v[62:65]
	v_mfma_f32_16x16x32_bf16 v[58:61], v[166:169], v[186:189], v[58:61]
	v_mfma_f32_16x16x32_bf16 v[110:113], v[170:173], v[198:201], v[78:81]
	v_mfma_f32_16x16x32_bf16 v[62:65], v[142:145], v[190:193], v[62:65]
	v_mfma_f32_16x16x32_bf16 v[58:61], v[170:173], v[190:193], v[58:61]
	s_setprio 0
	s_barrier
	s_nop 0
	ds_read_b128 v[78:81], v245 offset:49152
	ds_read_b128 v[92:95], v245 offset:50176
	ds_read_b128 v[102:105], v245 offset:51200
	ds_read_b128 v[118:121], v245 offset:52224
	ds_read_b128 v[122:125], v245 offset:53248
	ds_read_b128 v[186:189], v245 offset:54272
	ds_read_b128 v[190:193], v245 offset:55296
	ds_read_b128 v[194:197], v245 offset:56320
	s_mov_b32 m0, s64
	s_nop 0
	global_load_lds_dwordx4 v251, s[40:41]
	s_add_u32 m0, m0, 0x2000
	s_nop 0
	global_load_lds_dwordx4 v247, s[40:41]
	s_add_u32 s40, s84, 0x580080
	s_addc_u32 s41, s85, 0
	s_mov_b32 m0, s66
	s_nop 0
	global_load_lds_dwordx4 v251, s[40:41]
	s_add_u32 m0, m0, 0x2000
	s_nop 0
	global_load_lds_dwordx4 v247, s[40:41]
	s_nop 0
	s_mov_b32 m0, s65
	s_nop 0
	global_load_lds_dwordx4 v250, s[14:15]
	s_add_u32 m0, m0, 0x2000
	s_nop 0
	global_load_lds_dwordx4 v246, s[14:15]
	s_waitcnt vmcnt(8)
	s_waitcnt lgkmcnt(0)
	s_barrier
	s_setprio 1
	s_waitcnt lgkmcnt(7)
	v_mfma_f32_16x16x32_bf16 v[38:41], v[162:165], v[78:81], v[38:41]
	v_mfma_f32_16x16x32_bf16 v[34:37], v[178:181], v[78:81], v[34:37]
	s_waitcnt lgkmcnt(5)
	v_mfma_f32_16x16x32_bf16 v[18:21], v[178:181], v[102:105], v[18:21]
	v_mfma_f32_16x16x32_bf16 v[26:29], v[162:165], v[102:105], v[26:29]
	s_waitcnt lgkmcnt(3)
	v_mfma_f32_16x16x32_bf16 v[6:9], v[162:165], v[122:125], v[6:9]
	v_mfma_f32_16x16x32_bf16 v[2:5], v[178:181], v[122:125], v[2:5]
	s_waitcnt lgkmcnt(1)
	v_mfma_f32_16x16x32_bf16 v[130:133], v[178:181], v[190:193], v[130:133]
	v_mfma_f32_16x16x32_bf16 v[106:109], v[162:165], v[190:193], v[106:109]
	v_mfma_f32_16x16x32_bf16 v[38:41], v[174:177], v[92:95], v[38:41]
	v_mfma_f32_16x16x32_bf16 v[34:37], v[182:185], v[92:95], v[34:37]
	v_mfma_f32_16x16x32_bf16 v[18:21], v[182:185], v[118:121], v[18:21]
	v_mfma_f32_16x16x32_bf16 v[26:29], v[174:177], v[118:121], v[26:29]
	v_mfma_f32_16x16x32_bf16 v[6:9], v[174:177], v[186:189], v[6:9]
	v_mfma_f32_16x16x32_bf16 v[2:5], v[182:185], v[186:189], v[2:5]
	s_waitcnt lgkmcnt(0)
	v_mfma_f32_16x16x32_bf16 v[162:165], v[182:185], v[194:197], v[130:133]
	v_mfma_f32_16x16x32_bf16 v[106:109], v[174:177], v[194:197], v[106:109]
	s_setprio 0
	s_setprio 1
	v_mfma_f32_16x16x32_bf16 v[46:49], v[138:141], v[78:81], v[46:49]
	v_mfma_f32_16x16x32_bf16 v[42:45], v[166:169], v[78:81], v[42:45]
	v_mfma_f32_16x16x32_bf16 v[78:81], v[138:141], v[190:193], v[114:117]
	v_mfma_f32_16x16x32_bf16 v[30:33], v[138:141], v[102:105], v[30:33]
	v_mfma_f32_16x16x32_bf16 v[22:25], v[166:169], v[102:105], v[22:25]
	v_mfma_f32_16x16x32_bf16 v[10:13], v[166:169], v[122:125], v[10:13]
	v_mfma_f32_16x16x32_bf16 v[14:17], v[138:141], v[122:125], v[14:17]
	v_mfma_f32_16x16x32_bf16 v[114:117], v[142:145], v[194:197], v[78:81]
	v_mfma_f32_16x16x32_bf16 v[78:81], v[166:169], v[190:193], v[134:137]
	v_mfma_f32_16x16x32_bf16 v[46:49], v[142:145], v[92:95], v[46:49]
	v_mfma_f32_16x16x32_bf16 v[42:45], v[170:173], v[92:95], v[42:45]
	v_mfma_f32_16x16x32_bf16 v[22:25], v[170:173], v[118:121], v[22:25]
	v_mfma_f32_16x16x32_bf16 v[30:33], v[142:145], v[118:121], v[30:33]
	v_mfma_f32_16x16x32_bf16 v[14:17], v[142:145], v[186:189], v[14:17]
	v_mfma_f32_16x16x32_bf16 v[10:13], v[170:173], v[186:189], v[10:13]
	v_mfma_f32_16x16x32_bf16 v[166:169], v[170:173], v[194:197], v[78:81]
	s_setprio 0
	s_barrier
	s_add_i32 s0, s0, 2
	s_add_u32 s51, s51, 0x100
	s_addc_u32 s52, s52, 0
	s_add_u32 s53, s53, 0x100
	s_addc_u32 s61, s61, 0
	s_add_u32 s42, s42, 0x100
	s_addc_u32 s43, s43, 0
	s_cmp_gt_u32 s0, 13
	s_cbranch_scc1 .LBB0_565

; #define PG8_STAGE(bufoff, gbase, voff) glds16s2((voff)[0], (voff)[1], (const void*)(gbase), ldsn + (unsigned)(bufoff))
; #define PG8_LDA(dst, b, h) do { _Pragma("unroll") for (int m = 0; m < 4; ++m) _Pragma("unroll") for (int k = 0; k < 2; ++k) dst[m][k] = *(const LAS bf16x8*)(lds + PG8_SA(b, h) + aoff + m * 2048 + k * 1024); } while (0)
; #define PG8_LDB(dst, b, h) do { _Pragma("unroll") for (int n = 0; n < 2; ++n) _Pragma("unroll") for (int k = 0; k < 2; ++k) dst[n][k] = *(const LAS bf16x8*)(lds + PG8_SB(b, h) + boff + n * 2048 + k * 1024); } while (0)
; #define PG8_MMA(ai, bj, At, Bt) do { __builtin_amdgcn_s_setprio(1); _Pragma("unroll") for (int m = 0; m < 4; ++m) _Pragma("unroll") for (int n = 0; n < 2; ++n) _Pragma("unroll") for (int k = 0; k < 2; ++k) \
;         acc[ai][bj][m][n] = __builtin_amdgcn_mfma_f32_16x16x32_bf16(Bt[n][k], At[m][k], acc[ai][bj][m][n], 0, 0, 0); __builtin_amdgcn_s_setprio(0); } while (0)
; template <class Epi, bool ALIGN_EPI, bool EARLY_DRAIN = true, class Pre = NoPre>
; __device__ __forceinline__ void gemm_phase(LAS unsigned char* lds, const Gemm g, const StaticOrder& S, const Epi& E, int wv, const Pre& pre = Pre()) {
;     ...
;             const bool last = (t == nt - 2);
;             const char* a1 = cA + (size_t)(t + 1) * kstep;
;             const char* a2 = last ? nA : cA + (size_t)(t + 2) * kstep; const char* b2 = last ? nB : cB + (size_t)(t + 2) * kstep;
;             const char* a3 = a2 + kstep; const char* b3 = b2 + kstep;
;             int lf_ = EARLY_DRAIN ? __builtin_amdgcn_readfirstlane(landed_flag) : landed_flag; if constexpr (EARLY_DRAIN) asm volatile("" : "+s"(lf_)); landed_flag = 0;
;             PG8_LDB(B0, 0, 0); PG8_LDB(B1, 0, 1); PG8_SCHED; PG8_LDA(At, 0, 0); PG8_STAGE(PG8_SA(1, 1), a1 + ahs, voffA);
;             if (!lf_) PG8_WAIT_V(8);
;             PG8_WAIT_L(0); PG8_BAR; PG8_MMA(0, 0, At, B0); PG8_MMA(0, 1, At, B1); PG8_BAR; PG8_SCHED;
;             PG8_LDA(At, 0, 1); PG8_STAGE(PG8_SB(0, 0), b2, voffB); PG8_STAGE(PG8_SB(0, 1), b2 + bhs, voffB); PG8_STAGE(PG8_SA(0, 0), a2, voffA);
;             if (!lf_) PG8_WAIT_V(8);
;             PG8_WAIT_L(0); PG8_BAR; PG8_MMA(1, 0, At, B0); PG8_MMA(1, 1, At, B1); PG8_BAR; PG8_SCHED;
;             PG8_LDB(B0, 1, 0); PG8_LDB(B1, 1, 1); PG8_SCHED; PG8_LDA(At, 1, 0); PG8_STAGE(PG8_SA(0, 1), a2 + ahs, voffA);
;             if (!lf_) PG8_WAIT_V(8);
.LBB0_561:
	s_waitcnt lgkmcnt(0)
	s_cmp_eq_u32 s0, 12
	s_cselect_b32 s87, s71, s52
	s_cselect_b32 s86, s70, s51
	s_cselect_b32 s85, s47, s61
	s_cselect_b32 s84, s50, s53
	s_barrier
	s_setprio 1
	s_waitcnt lgkmcnt(7)
	v_mfma_f32_16x16x32_bf16 v[70:73], v[130:133], v[102:105], v[70:73]
	v_mfma_f32_16x16x32_bf16 v[78:81], v[178:181], v[102:105], v[146:149]
	s_waitcnt lgkmcnt(5)
	v_mfma_f32_16x16x32_bf16 v[92:95], v[178:181], v[118:121], v[150:153]
	v_mfma_f32_16x16x32_bf16 v[74:77], v[130:133], v[118:121], v[74:77]
	s_waitcnt lgkmcnt(3)
	v_mfma_f32_16x16x32_bf16 v[82:85], v[130:133], v[194:197], v[82:85]
	v_mfma_f32_16x16x32_bf16 v[66:69], v[178:181], v[194:197], v[66:69]
	s_waitcnt lgkmcnt(1)
	v_mfma_f32_16x16x32_bf16 v[50:53], v[178:181], v[186:189], v[50:53]
	v_mfma_f32_16x16x32_bf16 v[54:57], v[130:133], v[186:189], v[54:57]
	v_mfma_f32_16x16x32_bf16 v[70:73], v[174:177], v[202:205], v[70:73]
	v_mfma_f32_16x16x32_bf16 v[78:81], v[182:185], v[202:205], v[78:81]
	v_mfma_f32_16x16x32_bf16 v[92:95], v[182:185], v[122:125], v[92:95]
	v_mfma_f32_16x16x32_bf16 v[74:77], v[174:177], v[122:125], v[74:77]
	v_mfma_f32_16x16x32_bf16 v[82:85], v[174:177], v[198:201], v[82:85]
	v_mfma_f32_16x16x32_bf16 v[66:69], v[182:185], v[198:201], v[66:69]
	s_waitcnt lgkmcnt(0)
	v_mfma_f32_16x16x32_bf16 v[50:53], v[182:185], v[190:193], v[50:53]
	v_mfma_f32_16x16x32_bf16 v[54:57], v[174:177], v[190:193], v[54:57]
	s_setprio 0
	s_setprio 1
	v_mfma_f32_16x16x32_bf16 v[96:99], v[134:137], v[118:121], v[98:101]
	v_mfma_f32_16x16x32_bf16 v[118:121], v[142:145], v[118:121], v[158:161]
	v_mfma_f32_16x16x32_bf16 v[86:89], v[134:137], v[102:105], v[88:91]
	v_mfma_f32_16x16x32_bf16 v[102:105], v[142:145], v[102:105], v[154:157]
	v_mfma_f32_16x16x32_bf16 v[96:99], v[138:141], v[122:125], v[96:99]
	v_mfma_f32_16x16x32_bf16 v[118:121], v[170:173], v[122:125], v[118:121]
	v_mfma_f32_16x16x32_bf16 v[122:125], v[134:137], v[194:197], v[126:129]
	v_mfma_f32_16x16x32_bf16 v[110:113], v[142:145], v[194:197], v[110:113]
	v_mfma_f32_16x16x32_bf16 v[58:61], v[142:145], v[186:189], v[58:61]
	v_mfma_f32_16x16x32_bf16 v[62:65], v[134:137], v[186:189], v[62:65]
	v_mfma_f32_16x16x32_bf16 v[86:89], v[138:141], v[202:205], v[86:89]
	v_mfma_f32_16x16x32_bf16 v[102:105], v[170:173], v[202:205], v[102:105]
	v_mfma_f32_16x16x32_bf16 v[110:113], v[170:173], v[198:201], v[110:113]
	v_mfma_f32_16x16x32_bf16 v[122:125], v[138:141], v[198:201], v[122:125]
	v_mfma_f32_16x16x32_bf16 v[62:65], v[138:141], v[190:193], v[62:65]
	v_mfma_f32_16x16x32_bf16 v[58:61], v[170:173], v[190:193], v[58:61]
	s_setprio 0
	s_barrier
	ds_read_b128 v[190:193], v245 offset:16384
	ds_read_b128 v[194:197], v245 offset:17408
	ds_read_b128 v[158:161], v245 offset:18432
	ds_read_b128 v[186:189], v245 offset:19456
	ds_read_b128 v[150:153], v245 offset:20480
	ds_read_b128 v[154:157], v245 offset:21504
	ds_read_b128 v[126:129], v245 offset:22528
	ds_read_b128 v[146:149], v245 offset:23552
	s_mov_b32 m0, s22
	s_nop 0
	global_load_lds_dwordx4 v251, s[84:85]
	s_add_u32 m0, m0, 0x2000
	s_nop 0
	global_load_lds_dwordx4 v247, s[84:85]
	s_add_u32 s14, s84, 0x580000
	s_addc_u32 s15, s85, 0
	s_mov_b32 m0, s23
	s_nop 0
	global_load_lds_dwordx4 v251, s[14:15]
	s_add_u32 m0, m0, 0x2000
	s_nop 0
	global_load_lds_dwordx4 v247, s[14:15]
	v_cndmask_b32_e64 v90, 0, 1, vcc
	s_mov_b32 m0, s13
	s_nop 0
	global_load_lds_dwordx4 v250, s[86:87]
	s_add_u32 m0, m0, 0x2000
	s_nop 0
	global_load_lds_dwordx4 v246, s[86:87]
	v_cmp_ne_u32_e64 s[40:41], 1, v90
	s_andn2_b64 vcc, exec, vcc
	s_cbranch_vccnz .LBB0_563
	s_waitcnt vmcnt(8)
.LBB0_563:
	s_waitcnt lgkmcnt(0)
	s_barrier
	s_setprio 1
	s_waitcnt lgkmcnt(7)
	v_mfma_f32_16x16x32_bf16 v[38:41], v[130:133], v[190:193], v[38:41]
	v_mfma_f32_16x16x32_bf16 v[34:37], v[178:181], v[190:193], v[34:37]
	s_waitcnt lgkmcnt(5)
	v_mfma_f32_16x16x32_bf16 v[18:21], v[178:181], v[158:161], v[18:21]
	v_mfma_f32_16x16x32_bf16 v[26:29], v[130:133], v[158:161], v[26:29]
	s_waitcnt lgkmcnt(3)
	v_mfma_f32_16x16x32_bf16 v[6:9], v[130:133], v[150:153], v[6:9]
	v_mfma_f32_16x16x32_bf16 v[2:5], v[178:181], v[150:153], v[2:5]
	s_waitcnt lgkmcnt(1)
	v_mfma_f32_16x16x32_bf16 v[106:109], v[130:133], v[126:129], v[106:109]
	v_mfma_f32_16x16x32_bf16 v[130:133], v[178:181], v[126:129], v[162:165]
	v_mfma_f32_16x16x32_bf16 v[38:41], v[174:177], v[194:197], v[38:41]
	v_mfma_f32_16x16x32_bf16 v[34:37], v[182:185], v[194:197], v[34:37]
	v_mfma_f32_16x16x32_bf16 v[18:21], v[182:185], v[186:189], v[18:21]
	v_mfma_f32_16x16x32_bf16 v[26:29], v[174:177], v[186:189], v[26:29]
	v_mfma_f32_16x16x32_bf16 v[6:9], v[174:177], v[154:157], v[6:9]
	v_mfma_f32_16x16x32_bf16 v[2:5], v[182:185], v[154:157], v[2:5]
	s_waitcnt lgkmcnt(0)
	v_mfma_f32_16x16x32_bf16 v[130:133], v[182:185], v[146:149], v[130:133]
	v_mfma_f32_16x16x32_bf16 v[106:109], v[174:177], v[146:149], v[106:109]
	s_setprio 0
	s_setprio 1
	v_mfma_f32_16x16x32_bf16 v[46:49], v[134:137], v[190:193], v[46:49]
	v_mfma_f32_16x16x32_bf16 v[42:45], v[142:145], v[190:193], v[42:45]
	v_mfma_f32_16x16x32_bf16 v[22:25], v[142:145], v[158:161], v[22:25]
	v_mfma_f32_16x16x32_bf16 v[30:33], v[134:137], v[158:161], v[30:33]
	v_mfma_f32_16x16x32_bf16 v[14:17], v[134:137], v[150:153], v[14:17]
	v_mfma_f32_16x16x32_bf16 v[10:13], v[142:145], v[150:153], v[10:13]
	v_mfma_f32_16x16x32_bf16 v[114:117], v[134:137], v[126:129], v[114:117]
	v_mfma_f32_16x16x32_bf16 v[126:129], v[142:145], v[126:129], v[166:169]
	v_mfma_f32_16x16x32_bf16 v[46:49], v[138:141], v[194:197], v[46:49]
	v_mfma_f32_16x16x32_bf16 v[42:45], v[170:173], v[194:197], v[42:45]
	v_mfma_f32_16x16x32_bf16 v[22:25], v[170:173], v[186:189], v[22:25]
	v_mfma_f32_16x16x32_bf16 v[30:33], v[138:141], v[186:189], v[30:33]
	v_mfma_f32_16x16x32_bf16 v[14:17], v[138:141], v[154:157], v[14:17]
	v_mfma_f32_16x16x32_bf16 v[10:13], v[170:173], v[154:157], v[10:13]
	v_mfma_f32_16x16x32_bf16 v[134:137], v[170:173], v[146:149], v[126:129]
	v_mfma_f32_16x16x32_bf16 v[114:117], v[138:141], v[146:149], v[114:117]
	s_setprio 0
	s_barrier
	ds_read_b128 v[162:165], v235
	ds_read_b128 v[174:177], v235 offset:1024
	ds_read_b128 v[178:181], v235 offset:2048
	ds_read_b128 v[182:185], v235 offset:3072
	ds_read_b128 v[138:141], v248
	ds_read_b128 v[142:145], v248 offset:1024
	ds_read_b128 v[166:169], v248 offset:2048
	ds_read_b128 v[170:173], v248 offset:3072
	ds_read_b128 v[154:157], v245 offset:32768
	ds_read_b128 v[202:205], v245 offset:33792
	ds_read_b128 v[126:129], v245 offset:34816
	ds_read_b128 v[158:161], v245 offset:35840
	ds_read_b128 v[194:197], v245 offset:36864
	ds_read_b128 v[198:201], v245 offset:37888
	ds_read_b128 v[186:189], v245 offset:38912
	ds_read_b128 v[190:193], v245 offset:39936
	s_add_u32 s14, s86, 0x2000
	s_addc_u32 s15, s87, 0
	s_mov_b32 m0, s45
	s_nop 0
	global_load_lds_dwordx4 v250, s[14:15]
	s_add_u32 m0, m0, 0x2000
	s_nop 0
	global_load_lds_dwordx4 v246, s[14:15]
	s_and_b64 vcc, exec, s[40:41]
	s_cbranch_vccnz .LBB0_558
	s_waitcnt vmcnt(8)
	s_branch .LBB0_558

; #define PG8_STAGE(bufoff, gbase, voff) glds16s2((voff)[0], (voff)[1], (const void*)(gbase), ldsn + (unsigned)(bufoff))
; #define PG8_LDA(dst, b, h) do { _Pragma("unroll") for (int m = 0; m < 4; ++m) _Pragma("unroll") for (int k = 0; k < 2; ++k) dst[m][k] = *(const LAS bf16x8*)(lds + PG8_SA(b, h) + aoff + m * 2048 + k * 1024); } while (0)
; #define PG8_LDB(dst, b, h) do { _Pragma("unroll") for (int n = 0; n < 2; ++n) _Pragma("unroll") for (int k = 0; k < 2; ++k) dst[n][k] = *(const LAS bf16x8*)(lds + PG8_SB(b, h) + boff + n * 2048 + k * 1024); } while (0)
; #define PG8_MMA(ai, bj, At, Bt) do { __builtin_amdgcn_s_setprio(1); _Pragma("unroll") for (int m = 0; m < 4; ++m) _Pragma("unroll") for (int n = 0; n < 2; ++n) _Pragma("unroll") for (int k = 0; k < 2; ++k) \
;         acc[ai][bj][m][n] = __builtin_amdgcn_mfma_f32_16x16x32_bf16(Bt[n][k], At[m][k], acc[ai][bj][m][n], 0, 0, 0); __builtin_amdgcn_s_setprio(0); } while (0)
; #define PG8_WAIT_V(n) asm volatile("s_waitcnt vmcnt(" #n ")" ::: "memory")
; #define PG8_WAIT_L(n) asm volatile("s_waitcnt lgkmcnt(" #n ")" ::: "memory")
; #define PG8_BAR __builtin_amdgcn_s_barrier()
; template <class Epi, bool ALIGN_EPI, bool EARLY_DRAIN = true, class Pre = NoPre>
; __device__ __forceinline__ void gemm_phase(LAS unsigned char* lds, const Gemm g, const StaticOrder& S, const Epi& E, int wv, const Pre& pre = Pre()) {
;     ...
;             const char* a1 = cA + (size_t)(t + 1) * kstep;
;             const char* a2 = last ? nA : cA + (size_t)(t + 2) * kstep; const char* b2 = last ? nB : cB + (size_t)(t + 2) * kstep;
;             const char* a3 = a2 + kstep; const char* b3 = b2 + kstep;
;             int lf_ = EARLY_DRAIN ? __builtin_amdgcn_readfirstlane(landed_flag) : landed_flag; if constexpr (EARLY_DRAIN) asm volatile("" : "+s"(lf_)); landed_flag = 0;
;             PG8_LDB(B0, 0, 0); PG8_LDB(B1, 0, 1); PG8_SCHED; PG8_LDA(At, 0, 0); PG8_STAGE(PG8_SA(1, 1), a1 + ahs, voffA);
;             if (!lf_) PG8_WAIT_V(8);
;             PG8_WAIT_L(0); PG8_BAR; PG8_MMA(0, 0, At, B0); PG8_MMA(0, 1, At, B1); PG8_BAR; PG8_SCHED;
;             PG8_LDA(At, 0, 1); PG8_STAGE(PG8_SB(0, 0), b2, voffB); PG8_STAGE(PG8_SB(0, 1), b2 + bhs, voffB); PG8_STAGE(PG8_SA(0, 0), a2, voffA);
;             if (!lf_) PG8_WAIT_V(8);
;             PG8_WAIT_L(0); PG8_BAR; PG8_MMA(1, 0, At, B0); PG8_MMA(1, 1, At, B1); PG8_BAR; PG8_SCHED;
.LBB0_690:
	v_add_u32_e32 v174, 0x10000, v201
	v_add_u32_e32 v190, 0x14000, v201
	ds_read_b128 v[146:149], v174
	ds_read_b128 v[158:161], v174 offset:1024
	ds_read_b128 v[166:169], v174 offset:2048
	ds_read_b128 v[174:177], v174 offset:3072
	ds_read_b128 v[178:181], v190
	ds_read_b128 v[182:185], v190 offset:1024
	ds_read_b128 v[186:189], v190 offset:2048
	ds_read_b128 v[190:193], v190 offset:3072
	s_cmp_eq_u32 s80, 40
	s_cselect_b32 s68, s30, s52
	s_cselect_b32 s69, s31, s53
	s_cselect_b32 s60, s34, s70
	s_cselect_b32 s61, s35, s71
	s_add_u32 s40, s68, 0x80
	s_addc_u32 s41, s69, 0
	ds_read_b128 v[194:197], v202
	ds_read_b128 v[204:207], v202 offset:1024
	ds_read_b128 v[208:211], v202 offset:2048
	ds_read_b128 v[212:215], v202 offset:3072
	ds_read_b128 v[216:219], v202 offset:4096
	ds_read_b128 v[220:223], v202 offset:5120
	ds_read_b128 v[224:227], v202 offset:6144
	ds_read_b128 v[228:231], v202 offset:7168
	s_mov_b32 m0, s27
	s_nop 0
	global_load_lds_dwordx4 v0, s[36:37]
	s_add_u32 m0, m0, 0x2000
	s_nop 0
	global_load_lds_dwordx4 v199, s[36:37]
	s_waitcnt vmcnt(8)
	s_waitcnt lgkmcnt(0)
	s_barrier
	s_setprio 1
	s_waitcnt lgkmcnt(7)
	v_mfma_f32_16x16x32_bf16 v[170:173], v[146:149], v[194:197], v[170:173]
	v_mfma_f32_16x16x32_bf16 v[162:165], v[166:169], v[194:197], v[162:165]
	s_waitcnt lgkmcnt(5)
	v_mfma_f32_16x16x32_bf16 v[138:141], v[166:169], v[208:211], v[138:141]
	v_mfma_f32_16x16x32_bf16 v[142:145], v[146:149], v[208:211], v[142:145]
	s_waitcnt lgkmcnt(3)
	v_mfma_f32_16x16x32_bf16 v[126:129], v[146:149], v[216:219], v[126:129]
	v_mfma_f32_16x16x32_bf16 v[122:125], v[166:169], v[216:219], v[122:125]
	s_waitcnt lgkmcnt(1)
	v_mfma_f32_16x16x32_bf16 v[98:101], v[166:169], v[224:227], v[98:101]
	v_mfma_f32_16x16x32_bf16 v[102:105], v[146:149], v[224:227], v[102:105]
	v_mfma_f32_16x16x32_bf16 v[170:173], v[158:161], v[204:207], v[170:173]
	v_mfma_f32_16x16x32_bf16 v[162:165], v[174:177], v[204:207], v[162:165]
	v_mfma_f32_16x16x32_bf16 v[138:141], v[174:177], v[212:215], v[138:141]
	v_mfma_f32_16x16x32_bf16 v[142:145], v[158:161], v[212:215], v[142:145]
	v_mfma_f32_16x16x32_bf16 v[126:129], v[158:161], v[220:223], v[126:129]
	v_mfma_f32_16x16x32_bf16 v[122:125], v[174:177], v[220:223], v[122:125]
	s_waitcnt lgkmcnt(0)
	v_mfma_f32_16x16x32_bf16 v[98:101], v[174:177], v[228:231], v[98:101]
	v_mfma_f32_16x16x32_bf16 v[102:105], v[158:161], v[228:231], v[102:105]
	s_setprio 0
	s_setprio 1
	v_mfma_f32_16x16x32_bf16 v[154:157], v[178:181], v[194:197], v[154:157]
	v_mfma_f32_16x16x32_bf16 v[150:153], v[186:189], v[194:197], v[150:153]
	v_mfma_f32_16x16x32_bf16 v[130:133], v[186:189], v[208:211], v[130:133]
	v_mfma_f32_16x16x32_bf16 v[134:137], v[178:181], v[208:211], v[134:137]
	v_mfma_f32_16x16x32_bf16 v[114:117], v[178:181], v[216:219], v[114:117]
	v_mfma_f32_16x16x32_bf16 v[106:109], v[186:189], v[216:219], v[106:109]
	v_mfma_f32_16x16x32_bf16 v[82:85], v[186:189], v[224:227], v[82:85]
	v_mfma_f32_16x16x32_bf16 v[86:89], v[178:181], v[224:227], v[86:89]
	v_mfma_f32_16x16x32_bf16 v[154:157], v[182:185], v[204:207], v[154:157]
	v_mfma_f32_16x16x32_bf16 v[150:153], v[190:193], v[204:207], v[150:153]
	v_mfma_f32_16x16x32_bf16 v[130:133], v[190:193], v[212:215], v[130:133]
	v_mfma_f32_16x16x32_bf16 v[134:137], v[182:185], v[212:215], v[134:137]
	v_mfma_f32_16x16x32_bf16 v[114:117], v[182:185], v[220:223], v[114:117]
	v_mfma_f32_16x16x32_bf16 v[106:109], v[190:193], v[220:223], v[106:109]
	v_mfma_f32_16x16x32_bf16 v[82:85], v[190:193], v[228:231], v[82:85]
	v_mfma_f32_16x16x32_bf16 v[86:89], v[182:185], v[228:231], v[86:89]
	s_setprio 0
	s_barrier
	ds_read_b128 v[194:197], v202 offset:16384
	ds_read_b128 v[204:207], v202 offset:17408
	ds_read_b128 v[208:211], v202 offset:18432
	ds_read_b128 v[212:215], v202 offset:19456
	ds_read_b128 v[216:219], v202 offset:20480
	ds_read_b128 v[220:223], v202 offset:21504
	ds_read_b128 v[224:227], v202 offset:22528
	ds_read_b128 v[228:231], v202 offset:23552
	s_mov_b32 m0, s10
	s_nop 0
	global_load_lds_dwordx4 v198, s[60:61]
	s_add_u32 m0, m0, 0x2000
	s_nop 0
	global_load_lds_dwordx4 v200, s[60:61]
	s_add_u32 s14, s60, 0xb0000
	s_addc_u32 s15, s61, 0
	s_mov_b32 m0, s12
	s_nop 0
	global_load_lds_dwordx4 v198, s[14:15]
	s_add_u32 m0, m0, 0x2000
	s_nop 0
	global_load_lds_dwordx4 v200, s[14:15]
	s_nop 0
	s_mov_b32 m0, s5
	s_nop 0
	global_load_lds_dwordx4 v0, s[68:69]
	s_add_u32 m0, m0, 0x2000
	s_nop 0
	global_load_lds_dwordx4 v199, s[68:69]
	s_waitcnt vmcnt(8)
	s_waitcnt lgkmcnt(0)
	s_barrier
; #define PG8_STAGE(bufoff, gbase, voff) glds16s2((voff)[0], (voff)[1], (const void*)(gbase), ldsn + (unsigned)(bufoff))
; #define PG8_LDA(dst, b, h) do { _Pragma("unroll") for (int m = 0; m < 4; ++m) _Pragma("unroll") for (int k = 0; k < 2; ++k) dst[m][k] = *(const LAS bf16x8*)(lds + PG8_SA(b, h) + aoff + m * 2048 + k * 1024); } while (0)
; #define PG8_LDB(dst, b, h) do { _Pragma("unroll") for (int n = 0; n < 2; ++n) _Pragma("unroll") for (int k = 0; k < 2; ++k) dst[n][k] = *(const LAS bf16x8*)(lds + PG8_SB(b, h) + boff + n * 2048 + k * 1024); } while (0)
; #define PG8_MMA(ai, bj, At, Bt) do { __builtin_amdgcn_s_setprio(1); _Pragma("unroll") for (int m = 0; m < 4; ++m) _Pragma("unroll") for (int n = 0; n < 2; ++n) _Pragma("unroll") for (int k = 0; k < 2; ++k) \
;         acc[ai][bj][m][n] = __builtin_amdgcn_mfma_f32_16x16x32_bf16(Bt[n][k], At[m][k], acc[ai][bj][m][n], 0, 0, 0); __builtin_amdgcn_s_setprio(0); } while (0)
; #define PG8_WAIT_V(n) asm volatile("s_waitcnt vmcnt(" #n ")" ::: "memory")
; #define PG8_WAIT_L(n) asm volatile("s_waitcnt lgkmcnt(" #n ")" ::: "memory")
; #define PG8_BAR __builtin_amdgcn_s_barrier()
; #define PG8_SCHED __builtin_amdgcn_sched_barrier(0)
; template <class Epi, bool ALIGN_EPI, bool EARLY_DRAIN = true, class Pre = NoPre>
; __device__ __forceinline__ void gemm_phase(LAS unsigned char* lds, const Gemm g, const StaticOrder& S, const Epi& E, int wv, const Pre& pre = Pre()) {
;     ...
;             PG8_WAIT_L(0); PG8_BAR; PG8_MMA(1, 0, At, B0); PG8_MMA(1, 1, At, B1); PG8_BAR; PG8_SCHED;
;             PG8_LDB(B0, 1, 0); PG8_LDB(B1, 1, 1); PG8_SCHED; PG8_LDA(At, 1, 0); PG8_STAGE(PG8_SA(0, 1), a2 + ahs, voffA);
;             if (!lf_) PG8_WAIT_V(8);
;             PG8_WAIT_L(0); PG8_BAR; PG8_MMA(0, 0, At, B0); PG8_MMA(0, 1, At, B1); PG8_BAR; PG8_SCHED;
	s_setprio 1
	s_waitcnt lgkmcnt(7)
	v_mfma_f32_16x16x32_bf16 v[74:77], v[146:149], v[194:197], v[74:77]
	v_mfma_f32_16x16x32_bf16 v[70:73], v[166:169], v[194:197], v[70:73]
	s_waitcnt lgkmcnt(5)
	v_mfma_f32_16x16x32_bf16 v[46:49], v[166:169], v[208:211], v[46:49]
	v_mfma_f32_16x16x32_bf16 v[50:53], v[146:149], v[208:211], v[50:53]
	s_waitcnt lgkmcnt(3)
	v_mfma_f32_16x16x32_bf16 v[30:33], v[146:149], v[216:219], v[30:33]
	v_mfma_f32_16x16x32_bf16 v[26:29], v[166:169], v[216:219], v[26:29]
	s_waitcnt lgkmcnt(1)
	v_mfma_f32_16x16x32_bf16 v[10:13], v[166:169], v[224:227], v[10:13]
	v_mfma_f32_16x16x32_bf16 v[14:17], v[146:149], v[224:227], v[14:17]
	v_mfma_f32_16x16x32_bf16 v[74:77], v[158:161], v[204:207], v[74:77]
	v_mfma_f32_16x16x32_bf16 v[70:73], v[174:177], v[204:207], v[70:73]
	v_mfma_f32_16x16x32_bf16 v[46:49], v[174:177], v[212:215], v[46:49]
	v_mfma_f32_16x16x32_bf16 v[50:53], v[158:161], v[212:215], v[50:53]
	v_mfma_f32_16x16x32_bf16 v[30:33], v[158:161], v[220:223], v[30:33]
	v_mfma_f32_16x16x32_bf16 v[26:29], v[174:177], v[220:223], v[26:29]
	s_waitcnt lgkmcnt(0)
	v_mfma_f32_16x16x32_bf16 v[10:13], v[174:177], v[228:231], v[10:13]
	v_mfma_f32_16x16x32_bf16 v[14:17], v[158:161], v[228:231], v[14:17]
	s_setprio 0
	s_setprio 1
	v_mfma_f32_16x16x32_bf16 v[62:65], v[178:181], v[194:197], v[62:65]
	v_mfma_f32_16x16x32_bf16 v[58:61], v[186:189], v[194:197], v[58:61]
	v_mfma_f32_16x16x32_bf16 v[34:37], v[186:189], v[208:211], v[34:37]
	v_mfma_f32_16x16x32_bf16 v[38:41], v[178:181], v[208:211], v[38:41]
	v_mfma_f32_16x16x32_bf16 v[22:25], v[178:181], v[216:219], v[22:25]
	v_mfma_f32_16x16x32_bf16 v[18:21], v[186:189], v[216:219], v[18:21]
	v_mfma_f32_16x16x32_bf16 v[2:5], v[186:189], v[224:227], v[2:5]
	v_mfma_f32_16x16x32_bf16 v[6:9], v[178:181], v[224:227], v[6:9]
	v_mfma_f32_16x16x32_bf16 v[62:65], v[182:185], v[204:207], v[62:65]
	v_mfma_f32_16x16x32_bf16 v[58:61], v[190:193], v[204:207], v[58:61]
	v_mfma_f32_16x16x32_bf16 v[34:37], v[190:193], v[212:215], v[34:37]
	v_mfma_f32_16x16x32_bf16 v[38:41], v[182:185], v[212:215], v[38:41]
	v_mfma_f32_16x16x32_bf16 v[22:25], v[182:185], v[220:223], v[22:25]
	v_mfma_f32_16x16x32_bf16 v[18:21], v[190:193], v[220:223], v[18:21]
	v_mfma_f32_16x16x32_bf16 v[2:5], v[190:193], v[228:231], v[2:5]
	v_mfma_f32_16x16x32_bf16 v[6:9], v[182:185], v[228:231], v[6:9]
	s_setprio 0
	s_barrier
	v_add_u32_e32 v174, 0x18000, v201
	v_add_u32_e32 v190, 0x1c000, v201
	ds_read_b128 v[146:149], v174
	ds_read_b128 v[158:161], v174 offset:1024
	ds_read_b128 v[166:169], v174 offset:2048
	ds_read_b128 v[174:177], v174 offset:3072
	ds_read_b128 v[178:181], v190
	ds_read_b128 v[182:185], v190 offset:1024
	ds_read_b128 v[186:189], v190 offset:2048
	ds_read_b128 v[190:193], v190 offset:3072
	ds_read_b128 v[194:197], v202 offset:32768
	ds_read_b128 v[204:207], v202 offset:33792
	ds_read_b128 v[208:211], v202 offset:34816
	ds_read_b128 v[212:215], v202 offset:35840
	ds_read_b128 v[216:219], v202 offset:36864
	ds_read_b128 v[220:223], v202 offset:37888
	ds_read_b128 v[224:227], v202 offset:38912
	ds_read_b128 v[228:231], v202 offset:39936
	s_add_u32 s14, s68, 0xb0000
	s_addc_u32 s15, s69, 0
	s_mov_b32 m0, s13
	s_nop 0
	global_load_lds_dwordx4 v0, s[14:15]
	s_add_u32 m0, m0, 0x2000
	s_nop 0
	global_load_lds_dwordx4 v199, s[14:15]
	s_waitcnt vmcnt(8)
	s_waitcnt lgkmcnt(0)
	s_barrier
	s_setprio 1
	s_waitcnt lgkmcnt(7)
	v_mfma_f32_16x16x32_bf16 v[170:173], v[146:149], v[194:197], v[170:173]
	v_mfma_f32_16x16x32_bf16 v[162:165], v[166:169], v[194:197], v[162:165]
	s_waitcnt lgkmcnt(5)
	v_mfma_f32_16x16x32_bf16 v[138:141], v[166:169], v[208:211], v[138:141]
	v_mfma_f32_16x16x32_bf16 v[142:145], v[146:149], v[208:211], v[142:145]
	s_waitcnt lgkmcnt(3)
	v_mfma_f32_16x16x32_bf16 v[126:129], v[146:149], v[216:219], v[126:129]
	v_mfma_f32_16x16x32_bf16 v[122:125], v[166:169], v[216:219], v[122:125]
	s_waitcnt lgkmcnt(1)
	v_mfma_f32_16x16x32_bf16 v[98:101], v[166:169], v[224:227], v[98:101]
	v_mfma_f32_16x16x32_bf16 v[102:105], v[146:149], v[224:227], v[102:105]
	v_mfma_f32_16x16x32_bf16 v[170:173], v[158:161], v[204:207], v[170:173]
	v_mfma_f32_16x16x32_bf16 v[162:165], v[174:177], v[204:207], v[162:165]
	v_mfma_f32_16x16x32_bf16 v[138:141], v[174:177], v[212:215], v[138:141]
	v_mfma_f32_16x16x32_bf16 v[142:145], v[158:161], v[212:215], v[142:145]
	v_mfma_f32_16x16x32_bf16 v[126:129], v[158:161], v[220:223], v[126:129]
	v_mfma_f32_16x16x32_bf16 v[122:125], v[174:177], v[220:223], v[122:125]
	s_waitcnt lgkmcnt(0)
	v_mfma_f32_16x16x32_bf16 v[98:101], v[174:177], v[228:231], v[98:101]
	v_mfma_f32_16x16x32_bf16 v[102:105], v[158:161], v[228:231], v[102:105]
	s_setprio 0
	s_setprio 1
	v_mfma_f32_16x16x32_bf16 v[154:157], v[178:181], v[194:197], v[154:157]
	v_mfma_f32_16x16x32_bf16 v[150:153], v[186:189], v[194:197], v[150:153]
	v_mfma_f32_16x16x32_bf16 v[130:133], v[186:189], v[208:211], v[130:133]
	v_mfma_f32_16x16x32_bf16 v[134:137], v[178:181], v[208:211], v[134:137]
	v_mfma_f32_16x16x32_bf16 v[114:117], v[178:181], v[216:219], v[114:117]
	v_mfma_f32_16x16x32_bf16 v[106:109], v[186:189], v[216:219], v[106:109]
	v_mfma_f32_16x16x32_bf16 v[82:85], v[186:189], v[224:227], v[82:85]
	v_mfma_f32_16x16x32_bf16 v[86:89], v[178:181], v[224:227], v[86:89]
	v_mfma_f32_16x16x32_bf16 v[154:157], v[182:185], v[204:207], v[154:157]
	v_mfma_f32_16x16x32_bf16 v[150:153], v[190:193], v[204:207], v[150:153]
	v_mfma_f32_16x16x32_bf16 v[130:133], v[190:193], v[212:215], v[130:133]
	v_mfma_f32_16x16x32_bf16 v[134:137], v[182:185], v[212:215], v[134:137]
	v_mfma_f32_16x16x32_bf16 v[114:117], v[182:185], v[220:223], v[114:117]
	v_mfma_f32_16x16x32_bf16 v[106:109], v[190:193], v[220:223], v[106:109]
	v_mfma_f32_16x16x32_bf16 v[82:85], v[190:193], v[228:231], v[82:85]
	v_mfma_f32_16x16x32_bf16 v[86:89], v[182:185], v[228:231], v[86:89]
	s_setprio 0
	s_barrier
; #define PG8_STAGE(bufoff, gbase, voff) glds16s2((voff)[0], (voff)[1], (const void*)(gbase), ldsn + (unsigned)(bufoff))
; #define PG8_LDA(dst, b, h) do { _Pragma("unroll") for (int m = 0; m < 4; ++m) _Pragma("unroll") for (int k = 0; k < 2; ++k) dst[m][k] = *(const LAS bf16x8*)(lds + PG8_SA(b, h) + aoff + m * 2048 + k * 1024); } while (0)
; #define PG8_MMA(ai, bj, At, Bt) do { __builtin_amdgcn_s_setprio(1); _Pragma("unroll") for (int m = 0; m < 4; ++m) _Pragma("unroll") for (int n = 0; n < 2; ++n) _Pragma("unroll") for (int k = 0; k < 2; ++k) \
;         acc[ai][bj][m][n] = __builtin_amdgcn_mfma_f32_16x16x32_bf16(Bt[n][k], At[m][k], acc[ai][bj][m][n], 0, 0, 0); __builtin_amdgcn_s_setprio(0); } while (0)
; #define PG8_WAIT_V(n) asm volatile("s_waitcnt vmcnt(" #n ")" ::: "memory")
; #define PG8_WAIT_L(n) asm volatile("s_waitcnt lgkmcnt(" #n ")" ::: "memory")
; #define PG8_BAR __builtin_amdgcn_s_barrier()
; #define PG8_SCHED __builtin_amdgcn_sched_barrier(0)
; template <class Epi, bool ALIGN_EPI, bool EARLY_DRAIN = true, class Pre = NoPre>
; __device__ __forceinline__ void gemm_phase(LAS unsigned char* lds, const Gemm g, const StaticOrder& S, const Epi& E, int wv, const Pre& pre = Pre()) {
;     ...
;             PG8_LDA(At, 1, 1); PG8_STAGE(PG8_SB(1, 0), b3, voffB); PG8_STAGE(PG8_SB(1, 1), b3 + bhs, voffB); PG8_STAGE(PG8_SA(1, 0), a3, voffA);
;             PG8_WAIT_V(8); PG8_WAIT_L(0); PG8_BAR; PG8_MMA(1, 0, At, B0); PG8_MMA(1, 1, At, B1); PG8_BAR; PG8_SCHED;
;         }
;         }
;         if constexpr (ALIGN_EPI) { if (wr == 0) PG8_BAR; }
	ds_read_b128 v[194:197], v202 offset:49152
	ds_read_b128 v[204:207], v202 offset:50176
	ds_read_b128 v[208:211], v202 offset:51200
	ds_read_b128 v[212:215], v202 offset:52224
	ds_read_b128 v[216:219], v202 offset:53248
	ds_read_b128 v[220:223], v202 offset:54272
	ds_read_b128 v[224:227], v202 offset:55296
	ds_read_b128 v[228:231], v202 offset:56320
	s_add_u32 s14, s60, 0x80
	s_addc_u32 s15, s61, 0
	s_mov_b32 m0, s24
	s_nop 0
	global_load_lds_dwordx4 v198, s[14:15]
	s_add_u32 m0, m0, 0x2000
	s_nop 0
	global_load_lds_dwordx4 v200, s[14:15]
	s_add_u32 s14, s60, 0xb0080
	s_addc_u32 s15, s61, 0
	s_mov_b32 m0, s26
	s_nop 0
	global_load_lds_dwordx4 v198, s[14:15]
	s_add_u32 m0, m0, 0x2000
	s_nop 0
	global_load_lds_dwordx4 v200, s[14:15]
	s_nop 0
	s_mov_b32 m0, s25
	s_nop 0
	global_load_lds_dwordx4 v0, s[40:41]
	s_add_u32 m0, m0, 0x2000
	s_nop 0
	global_load_lds_dwordx4 v199, s[40:41]
	s_waitcnt vmcnt(8)
	s_waitcnt lgkmcnt(0)
	s_barrier
	s_setprio 1
	s_waitcnt lgkmcnt(7)
	v_mfma_f32_16x16x32_bf16 v[74:77], v[146:149], v[194:197], v[74:77]
	v_mfma_f32_16x16x32_bf16 v[70:73], v[166:169], v[194:197], v[70:73]
	s_waitcnt lgkmcnt(5)
	v_mfma_f32_16x16x32_bf16 v[46:49], v[166:169], v[208:211], v[46:49]
	v_mfma_f32_16x16x32_bf16 v[50:53], v[146:149], v[208:211], v[50:53]
	s_waitcnt lgkmcnt(3)
	v_mfma_f32_16x16x32_bf16 v[30:33], v[146:149], v[216:219], v[30:33]
	v_mfma_f32_16x16x32_bf16 v[26:29], v[166:169], v[216:219], v[26:29]
	s_waitcnt lgkmcnt(1)
	v_mfma_f32_16x16x32_bf16 v[10:13], v[166:169], v[224:227], v[10:13]
	v_mfma_f32_16x16x32_bf16 v[14:17], v[146:149], v[224:227], v[14:17]
	v_mfma_f32_16x16x32_bf16 v[74:77], v[158:161], v[204:207], v[74:77]
	v_mfma_f32_16x16x32_bf16 v[70:73], v[174:177], v[204:207], v[70:73]
	v_mfma_f32_16x16x32_bf16 v[46:49], v[174:177], v[212:215], v[46:49]
	v_mfma_f32_16x16x32_bf16 v[50:53], v[158:161], v[212:215], v[50:53]
	v_mfma_f32_16x16x32_bf16 v[30:33], v[158:161], v[220:223], v[30:33]
	v_mfma_f32_16x16x32_bf16 v[26:29], v[174:177], v[220:223], v[26:29]
	s_waitcnt lgkmcnt(0)
	v_mfma_f32_16x16x32_bf16 v[10:13], v[174:177], v[228:231], v[10:13]
	v_mfma_f32_16x16x32_bf16 v[14:17], v[158:161], v[228:231], v[14:17]
	s_setprio 0
	s_setprio 1
	v_mfma_f32_16x16x32_bf16 v[62:65], v[178:181], v[194:197], v[62:65]
	v_mfma_f32_16x16x32_bf16 v[58:61], v[186:189], v[194:197], v[58:61]
	v_mfma_f32_16x16x32_bf16 v[34:37], v[186:189], v[208:211], v[34:37]
	v_mfma_f32_16x16x32_bf16 v[38:41], v[178:181], v[208:211], v[38:41]
	v_mfma_f32_16x16x32_bf16 v[22:25], v[178:181], v[216:219], v[22:25]
	v_mfma_f32_16x16x32_bf16 v[18:21], v[186:189], v[216:219], v[18:21]
	v_mfma_f32_16x16x32_bf16 v[2:5], v[186:189], v[224:227], v[2:5]
	v_mfma_f32_16x16x32_bf16 v[6:9], v[178:181], v[224:227], v[6:9]
	v_mfma_f32_16x16x32_bf16 v[62:65], v[182:185], v[204:207], v[62:65]
	v_mfma_f32_16x16x32_bf16 v[58:61], v[190:193], v[204:207], v[58:61]
	v_mfma_f32_16x16x32_bf16 v[34:37], v[190:193], v[212:215], v[34:37]
	v_mfma_f32_16x16x32_bf16 v[38:41], v[182:185], v[212:215], v[38:41]
	v_mfma_f32_16x16x32_bf16 v[22:25], v[182:185], v[220:223], v[22:25]
	v_mfma_f32_16x16x32_bf16 v[18:21], v[190:193], v[220:223], v[18:21]
	v_mfma_f32_16x16x32_bf16 v[2:5], v[190:193], v[228:231], v[2:5]
	v_mfma_f32_16x16x32_bf16 v[6:9], v[182:185], v[228:231], v[6:9]
	s_setprio 0
	s_barrier
	s_add_i32 s80, s80, 2
	s_add_u32 s52, s52, 0x100
	s_addc_u32 s53, s53, 0
	s_add_u32 s70, s70, 0x100
	s_addc_u32 s71, s71, 0
	s_add_u32 s36, s36, 0x100
	s_addc_u32 s37, s37, 0
	s_cmp_gt_u32 s80, 41
	s_cbranch_scc0 .LBB0_690
	s_and_b64 vcc, exec, s[18:19]
	s_cbranch_vccz .LBB0_693
	s_barrier

; #define PG8_STAGE(bufoff, gbase, voff) glds16s2((voff)[0], (voff)[1], (const void*)(gbase), ldsn + (unsigned)(bufoff))
; #define PG8_LDA(dst, b, h) do { _Pragma("unroll") for (int m = 0; m < 4; ++m) _Pragma("unroll") for (int k = 0; k < 2; ++k) dst[m][k] = *(const LAS bf16x8*)(lds + PG8_SA(b, h) + aoff + m * 2048 + k * 1024); } while (0)
; #define PG8_LDB(dst, b, h) do { _Pragma("unroll") for (int n = 0; n < 2; ++n) _Pragma("unroll") for (int k = 0; k < 2; ++k) dst[n][k] = *(const LAS bf16x8*)(lds + PG8_SB(b, h) + boff + n * 2048 + k * 1024); } while (0)
; #define PG8_MMA(ai, bj, At, Bt) do { __builtin_amdgcn_s_setprio(1); _Pragma("unroll") for (int m = 0; m < 4; ++m) _Pragma("unroll") for (int n = 0; n < 2; ++n) _Pragma("unroll") for (int k = 0; k < 2; ++k) \
;         acc[ai][bj][m][n] = __builtin_amdgcn_mfma_f32_16x16x32_bf16(Bt[n][k], At[m][k], acc[ai][bj][m][n], 0, 0, 0); __builtin_amdgcn_s_setprio(0); } while (0)
; #define PG8_WAIT_V(n) asm volatile("s_waitcnt vmcnt(" #n ")" ::: "memory")
; #define PG8_WAIT_L(n) asm volatile("s_waitcnt lgkmcnt(" #n ")" ::: "memory")
; #define PG8_BAR __builtin_amdgcn_s_barrier()
; #define PG8_SCHED __builtin_amdgcn_sched_barrier(0)
; template <class Epi, bool ALIGN_EPI, bool EARLY_DRAIN = true, class Pre = NoPre>
; __device__ __forceinline__ void gemm_phase(LAS unsigned char* lds, const Gemm g, const StaticOrder& S, const Epi& E, int wv, const Pre& pre = Pre()) {
;     ...
;             PG8_LDB(B0, 0, 0); PG8_LDB(B1, 0, 1); PG8_SCHED; PG8_LDA(At, 0, 0); PG8_STAGE(PG8_SA(1, 1), a1 + ahs, voffA);
;             if (!lf_) PG8_WAIT_V(8);
;             PG8_WAIT_L(0); PG8_BAR; PG8_MMA(0, 0, At, B0); PG8_MMA(0, 1, At, B1); PG8_BAR; PG8_SCHED;
;             PG8_LDA(At, 0, 1); PG8_STAGE(PG8_SB(0, 0), b2, voffB); PG8_STAGE(PG8_SB(0, 1), b2 + bhs, voffB); PG8_STAGE(PG8_SA(0, 0), a2, voffA);
;             if (!lf_) PG8_WAIT_V(8);
.LBB0_729:
	s_add_u32 s14, s70, 0x100
	s_waitcnt lgkmcnt(0)
	s_addc_u32 s15, s71, 0
	s_add_u32 s24, s68, 0x100
	s_addc_u32 s25, s69, 0
	s_barrier
	s_setprio 1
	s_waitcnt lgkmcnt(7)
	v_mfma_f32_16x16x32_bf16 v[2:5], v[82:85], v[38:41], 0
	v_mfma_f32_16x16x32_bf16 v[6:9], v[90:93], v[38:41], 0
	s_waitcnt lgkmcnt(5)
	v_mfma_f32_16x16x32_bf16 v[10:13], v[82:85], v[46:49], 0
	v_mfma_f32_16x16x32_bf16 v[14:17], v[90:93], v[46:49], 0
	s_waitcnt lgkmcnt(3)
	v_mfma_f32_16x16x32_bf16 v[18:21], v[82:85], v[54:57], 0
	v_mfma_f32_16x16x32_bf16 v[22:25], v[90:93], v[54:57], 0
	s_waitcnt lgkmcnt(1)
	v_mfma_f32_16x16x32_bf16 v[26:29], v[82:85], v[62:65], 0
	v_mfma_f32_16x16x32_bf16 v[30:33], v[90:93], v[62:65], 0
	v_mfma_f32_16x16x32_bf16 v[2:5], v[86:89], v[42:45], v[2:5]
	v_mfma_f32_16x16x32_bf16 v[6:9], v[94:97], v[42:45], v[6:9]
	v_mfma_f32_16x16x32_bf16 v[14:17], v[94:97], v[50:53], v[14:17]
	v_mfma_f32_16x16x32_bf16 v[10:13], v[86:89], v[50:53], v[10:13]
	v_mfma_f32_16x16x32_bf16 v[18:21], v[86:89], v[58:61], v[18:21]
	v_mfma_f32_16x16x32_bf16 v[22:25], v[94:97], v[58:61], v[22:25]
	s_waitcnt lgkmcnt(0)
	v_mfma_f32_16x16x32_bf16 v[30:33], v[94:97], v[98:101], v[30:33]
	v_mfma_f32_16x16x32_bf16 v[26:29], v[86:89], v[98:101], v[26:29]
	s_setprio 0
	s_setprio 1
	v_mfma_f32_16x16x32_bf16 v[34:37], v[66:69], v[38:41], 0
	v_mfma_f32_16x16x32_bf16 v[38:41], v[74:77], v[38:41], 0
	v_mfma_f32_16x16x32_bf16 v[34:37], v[70:73], v[42:45], v[34:37]
	v_mfma_f32_16x16x32_bf16 v[38:41], v[78:81], v[42:45], v[38:41]
	v_mfma_f32_16x16x32_bf16 v[42:45], v[66:69], v[46:49], 0
	v_mfma_f32_16x16x32_bf16 v[46:49], v[74:77], v[46:49], 0
	v_mfma_f32_16x16x32_bf16 v[42:45], v[70:73], v[50:53], v[42:45]
	v_mfma_f32_16x16x32_bf16 v[46:49], v[78:81], v[50:53], v[46:49]
	v_mfma_f32_16x16x32_bf16 v[50:53], v[66:69], v[54:57], 0
	v_mfma_f32_16x16x32_bf16 v[54:57], v[74:77], v[54:57], 0
	v_mfma_f32_16x16x32_bf16 v[50:53], v[70:73], v[58:61], v[50:53]
	v_mfma_f32_16x16x32_bf16 v[54:57], v[78:81], v[58:61], v[54:57]
	v_mfma_f32_16x16x32_bf16 v[58:61], v[66:69], v[62:65], 0
	v_mfma_f32_16x16x32_bf16 v[62:65], v[74:77], v[62:65], 0
	v_mfma_f32_16x16x32_bf16 v[58:61], v[70:73], v[98:101], v[58:61]
	v_mfma_f32_16x16x32_bf16 v[62:65], v[78:81], v[98:101], v[62:65]
	s_setprio 0
	s_barrier
	ds_read_b128 v[154:157], v250 offset:16384
	ds_read_b128 v[162:165], v250 offset:17408
	ds_read_b128 v[130:133], v250 offset:18432
	ds_read_b128 v[146:149], v250 offset:19456
	ds_read_b128 v[110:113], v250 offset:20480
	ds_read_b128 v[118:121], v250 offset:21504
	ds_read_b128 v[102:105], v250 offset:22528
	ds_read_b128 v[106:109], v250 offset:23552
	s_mov_b32 m0, s12
	s_nop 0
	global_load_lds_dwordx4 v230, s[24:25]
	s_add_u32 m0, m0, 0x2000
	s_nop 0
	global_load_lds_dwordx4 v232, s[24:25]
	s_add_u32 s24, s68, 0xb0100
	s_addc_u32 s25, s69, 0
	s_mov_b32 m0, s13
	s_nop 0
	global_load_lds_dwordx4 v230, s[24:25]
	s_add_u32 m0, m0, 0x2000
	s_nop 0
	global_load_lds_dwordx4 v232, s[24:25]
	v_cndmask_b32_e64 v98, 0, 1, s[84:85]
	s_mov_b32 m0, s10
	s_nop 0
	global_load_lds_dwordx4 v0, s[14:15]
	s_add_u32 m0, m0, 0x2000
	s_nop 0
	global_load_lds_dwordx4 v231, s[14:15]
	v_cmp_ne_u32_e64 s[38:39], 1, v98
	s_andn2_b64 vcc, exec, s[84:85]
	s_cbranch_vccnz .LBB0_731
	s_waitcnt vmcnt(8)

; #define PG8_STAGE(bufoff, gbase, voff) glds16s2((voff)[0], (voff)[1], (const void*)(gbase), ldsn + (unsigned)(bufoff))
; #define PG8_LDA(dst, b, h) do { _Pragma("unroll") for (int m = 0; m < 4; ++m) _Pragma("unroll") for (int k = 0; k < 2; ++k) dst[m][k] = *(const LAS bf16x8*)(lds + PG8_SA(b, h) + aoff + m * 2048 + k * 1024); } while (0)
; #define PG8_MMA(ai, bj, At, Bt) do { __builtin_amdgcn_s_setprio(1); _Pragma("unroll") for (int m = 0; m < 4; ++m) _Pragma("unroll") for (int n = 0; n < 2; ++n) _Pragma("unroll") for (int k = 0; k < 2; ++k) \
;         acc[ai][bj][m][n] = __builtin_amdgcn_mfma_f32_16x16x32_bf16(Bt[n][k], At[m][k], acc[ai][bj][m][n], 0, 0, 0); __builtin_amdgcn_s_setprio(0); } while (0)
; #define PG8_WAIT_V(n) asm volatile("s_waitcnt vmcnt(" #n ")" ::: "memory")
; #define PG8_WAIT_L(n) asm volatile("s_waitcnt lgkmcnt(" #n ")" ::: "memory")
; #define PG8_BAR __builtin_amdgcn_s_barrier()
; #define PG8_SCHED __builtin_amdgcn_sched_barrier(0)
; template <class Epi, bool ALIGN_EPI, bool EARLY_DRAIN = true, class Pre = NoPre>
; __device__ __forceinline__ void gemm_phase(LAS unsigned char* lds, const Gemm g, const StaticOrder& S, const Epi& E, int wv, const Pre& pre = Pre()) {
;     ...
;             PG8_WAIT_L(0); PG8_BAR; PG8_MMA(0, 0, At, B0); PG8_MMA(0, 1, At, B1); PG8_BAR; PG8_SCHED;
;             PG8_LDA(At, 1, 1); PG8_STAGE(PG8_SB(1, 0), b3, voffB); PG8_STAGE(PG8_SB(1, 1), b3 + bhs, voffB); PG8_STAGE(PG8_SA(1, 0), a3, voffA);
;             PG8_WAIT_V(8); PG8_WAIT_L(0); PG8_BAR; PG8_MMA(1, 0, At, B0); PG8_MMA(1, 1, At, B1); PG8_BAR; PG8_SCHED;
;         }
.LBB0_734:
	s_add_u32 s14, s84, 0x80
	s_waitcnt lgkmcnt(0)
	s_addc_u32 s15, s85, 0
	s_add_u32 s38, s70, 0x80
	s_addc_u32 s39, s71, 0
	s_barrier
	s_setprio 1
	s_waitcnt lgkmcnt(7)
	v_mfma_f32_16x16x32_bf16 v[98:101], v[158:161], v[130:133], v[98:101]
	s_waitcnt lgkmcnt(6)
	v_mfma_f32_16x16x32_bf16 v[162:165], v[166:169], v[202:205], v[98:101]
	v_mfma_f32_16x16x32_bf16 v[98:101], v[170:173], v[130:133], v[114:117]
	v_mfma_f32_16x16x32_bf16 v[154:157], v[174:177], v[202:205], v[98:101]
	s_waitcnt lgkmcnt(5)
	v_mfma_f32_16x16x32_bf16 v[98:101], v[158:161], v[194:197], v[118:121]
	s_waitcnt lgkmcnt(4)
	v_mfma_f32_16x16x32_bf16 v[118:121], v[166:169], v[198:201], v[98:101]
	v_mfma_f32_16x16x32_bf16 v[98:101], v[170:173], v[194:197], v[110:113]
	s_waitcnt lgkmcnt(3)
	v_mfma_f32_16x16x32_bf16 v[94:97], v[158:161], v[186:189], v[94:97]
	v_mfma_f32_16x16x32_bf16 v[90:93], v[170:173], v[186:189], v[90:93]
	s_waitcnt lgkmcnt(1)
	v_mfma_f32_16x16x32_bf16 v[74:77], v[170:173], v[178:181], v[74:77]
	v_mfma_f32_16x16x32_bf16 v[78:81], v[158:161], v[178:181], v[78:81]
	v_mfma_f32_16x16x32_bf16 v[110:113], v[174:177], v[198:201], v[98:101]
	v_mfma_f32_16x16x32_bf16 v[94:97], v[166:169], v[190:193], v[94:97]
	v_mfma_f32_16x16x32_bf16 v[90:93], v[174:177], v[190:193], v[90:93]
	s_waitcnt lgkmcnt(0)
	v_mfma_f32_16x16x32_bf16 v[74:77], v[174:177], v[182:185], v[74:77]
	v_mfma_f32_16x16x32_bf16 v[78:81], v[166:169], v[182:185], v[78:81]
	s_setprio 0
	s_setprio 1
	v_mfma_f32_16x16x32_bf16 v[98:101], v[134:137], v[130:133], v[122:125]
	v_mfma_f32_16x16x32_bf16 v[146:149], v[138:141], v[202:205], v[98:101]
	v_mfma_f32_16x16x32_bf16 v[98:101], v[142:145], v[130:133], v[126:129]
	v_mfma_f32_16x16x32_bf16 v[130:133], v[150:153], v[202:205], v[98:101]
	v_mfma_f32_16x16x32_bf16 v[98:101], v[134:137], v[194:197], v[106:109]
	v_mfma_f32_16x16x32_bf16 v[106:109], v[138:141], v[198:201], v[98:101]
	v_mfma_f32_16x16x32_bf16 v[98:101], v[142:145], v[194:197], v[102:105]
	v_mfma_f32_16x16x32_bf16 v[86:89], v[134:137], v[186:189], v[86:89]
	v_mfma_f32_16x16x32_bf16 v[82:85], v[142:145], v[186:189], v[82:85]
	v_mfma_f32_16x16x32_bf16 v[66:69], v[142:145], v[178:181], v[66:69]
	v_mfma_f32_16x16x32_bf16 v[70:73], v[134:137], v[178:181], v[70:73]
	v_mfma_f32_16x16x32_bf16 v[102:105], v[150:153], v[198:201], v[98:101]
	v_mfma_f32_16x16x32_bf16 v[86:89], v[138:141], v[190:193], v[86:89]
	v_mfma_f32_16x16x32_bf16 v[82:85], v[150:153], v[190:193], v[82:85]
	v_mfma_f32_16x16x32_bf16 v[66:69], v[150:153], v[182:185], v[66:69]
	v_mfma_f32_16x16x32_bf16 v[70:73], v[138:141], v[182:185], v[70:73]
	s_setprio 0
	s_barrier
	ds_read_b128 v[98:101], v250 offset:49152
	ds_read_b128 v[114:117], v250 offset:50176
	ds_read_b128 v[122:125], v250 offset:51200
	ds_read_b128 v[126:129], v250 offset:52224
	ds_read_b128 v[178:181], v250 offset:53248
	ds_read_b128 v[182:185], v250 offset:54272
	ds_read_b128 v[186:189], v250 offset:55296
	ds_read_b128 v[190:193], v250 offset:56320
	s_mov_b32 m0, s64
	s_nop 0
	global_load_lds_dwordx4 v230, s[38:39]
	s_add_u32 m0, m0, 0x2000
	s_nop 0
	global_load_lds_dwordx4 v232, s[38:39]
	s_add_u32 s38, s70, 0xb0080
	s_addc_u32 s39, s71, 0
	s_mov_b32 m0, s66
	s_nop 0
	global_load_lds_dwordx4 v230, s[38:39]
	s_add_u32 m0, m0, 0x2000
	s_nop 0
	global_load_lds_dwordx4 v232, s[38:39]
	s_nop 0
	s_mov_b32 m0, s65
	s_nop 0
	global_load_lds_dwordx4 v0, s[14:15]
	s_add_u32 m0, m0, 0x2000
	s_nop 0
	global_load_lds_dwordx4 v231, s[14:15]
	s_waitcnt vmcnt(8)
	s_waitcnt lgkmcnt(0)
	s_barrier
	s_setprio 1
	s_waitcnt lgkmcnt(7)
	v_mfma_f32_16x16x32_bf16 v[62:65], v[158:161], v[98:101], v[62:65]
	v_mfma_f32_16x16x32_bf16 v[58:61], v[170:173], v[98:101], v[58:61]
	s_waitcnt lgkmcnt(5)
	v_mfma_f32_16x16x32_bf16 v[42:45], v[170:173], v[122:125], v[42:45]
	v_mfma_f32_16x16x32_bf16 v[46:49], v[158:161], v[122:125], v[46:49]
	s_waitcnt lgkmcnt(3)
	v_mfma_f32_16x16x32_bf16 v[30:33], v[158:161], v[178:181], v[30:33]
	v_mfma_f32_16x16x32_bf16 v[26:29], v[170:173], v[178:181], v[26:29]
	s_waitcnt lgkmcnt(1)
	v_mfma_f32_16x16x32_bf16 v[10:13], v[170:173], v[186:189], v[10:13]
	v_mfma_f32_16x16x32_bf16 v[14:17], v[158:161], v[186:189], v[14:17]
	v_mfma_f32_16x16x32_bf16 v[62:65], v[166:169], v[114:117], v[62:65]
	v_mfma_f32_16x16x32_bf16 v[58:61], v[174:177], v[114:117], v[58:61]
	v_mfma_f32_16x16x32_bf16 v[42:45], v[174:177], v[126:129], v[42:45]
	v_mfma_f32_16x16x32_bf16 v[46:49], v[166:169], v[126:129], v[46:49]
	v_mfma_f32_16x16x32_bf16 v[30:33], v[166:169], v[182:185], v[30:33]
	v_mfma_f32_16x16x32_bf16 v[26:29], v[174:177], v[182:185], v[26:29]
	s_waitcnt lgkmcnt(0)
	v_mfma_f32_16x16x32_bf16 v[10:13], v[174:177], v[190:193], v[10:13]
	v_mfma_f32_16x16x32_bf16 v[14:17], v[166:169], v[190:193], v[14:17]
	s_setprio 0
	s_setprio 1
	v_mfma_f32_16x16x32_bf16 v[54:57], v[134:137], v[98:101], v[54:57]
	v_mfma_f32_16x16x32_bf16 v[50:53], v[142:145], v[98:101], v[50:53]
	v_mfma_f32_16x16x32_bf16 v[34:37], v[142:145], v[122:125], v[34:37]
	v_mfma_f32_16x16x32_bf16 v[38:41], v[134:137], v[122:125], v[38:41]
	v_mfma_f32_16x16x32_bf16 v[22:25], v[134:137], v[178:181], v[22:25]
	v_mfma_f32_16x16x32_bf16 v[18:21], v[142:145], v[178:181], v[18:21]
	v_mfma_f32_16x16x32_bf16 v[2:5], v[142:145], v[186:189], v[2:5]
	v_mfma_f32_16x16x32_bf16 v[6:9], v[134:137], v[186:189], v[6:9]
	v_mfma_f32_16x16x32_bf16 v[54:57], v[138:141], v[114:117], v[54:57]
	v_mfma_f32_16x16x32_bf16 v[50:53], v[150:153], v[114:117], v[50:53]
	v_mfma_f32_16x16x32_bf16 v[34:37], v[150:153], v[126:129], v[34:37]
	v_mfma_f32_16x16x32_bf16 v[38:41], v[138:141], v[126:129], v[38:41]
	v_mfma_f32_16x16x32_bf16 v[22:25], v[138:141], v[182:185], v[22:25]
	v_mfma_f32_16x16x32_bf16 v[18:21], v[150:153], v[182:185], v[18:21]
	v_mfma_f32_16x16x32_bf16 v[2:5], v[150:153], v[190:193], v[2:5]
	v_mfma_f32_16x16x32_bf16 v[6:9], v[138:141], v[190:193], v[6:9]
	s_setprio 0
	s_barrier
	s_add_i32 s0, s0, 2
	s_add_u32 s19, s19, 0x100
	s_addc_u32 s24, s24, 0
	s_add_u32 s25, s25, 0x100
	s_addc_u32 s26, s26, 0
	s_add_u32 s68, s68, 0x100
	s_addc_u32 s69, s69, 0
	s_cmp_gt_u32 s0, 41
	s_cbranch_scc1 .LBB0_741

; #define PG8_STAGE(bufoff, gbase, voff) glds16s2((voff)[0], (voff)[1], (const void*)(gbase), ldsn + (unsigned)(bufoff))
; #define PG8_LDA(dst, b, h) do { _Pragma("unroll") for (int m = 0; m < 4; ++m) _Pragma("unroll") for (int k = 0; k < 2; ++k) dst[m][k] = *(const LAS bf16x8*)(lds + PG8_SA(b, h) + aoff + m * 2048 + k * 1024); } while (0)
; #define PG8_LDB(dst, b, h) do { _Pragma("unroll") for (int n = 0; n < 2; ++n) _Pragma("unroll") for (int k = 0; k < 2; ++k) dst[n][k] = *(const LAS bf16x8*)(lds + PG8_SB(b, h) + boff + n * 2048 + k * 1024); } while (0)
; #define PG8_MMA(ai, bj, At, Bt) do { __builtin_amdgcn_s_setprio(1); _Pragma("unroll") for (int m = 0; m < 4; ++m) _Pragma("unroll") for (int n = 0; n < 2; ++n) _Pragma("unroll") for (int k = 0; k < 2; ++k) \
;         acc[ai][bj][m][n] = __builtin_amdgcn_mfma_f32_16x16x32_bf16(Bt[n][k], At[m][k], acc[ai][bj][m][n], 0, 0, 0); __builtin_amdgcn_s_setprio(0); } while (0)
; template <class Epi, bool ALIGN_EPI, bool EARLY_DRAIN = true, class Pre = NoPre>
; __device__ __forceinline__ void gemm_phase(LAS unsigned char* lds, const Gemm g, const StaticOrder& S, const Epi& E, int wv, const Pre& pre = Pre()) {
;     ...
;             const bool last = (t == nt - 2);
;             const char* a1 = cA + (size_t)(t + 1) * kstep;
;             const char* a2 = last ? nA : cA + (size_t)(t + 2) * kstep; const char* b2 = last ? nB : cB + (size_t)(t + 2) * kstep;
;             const char* a3 = a2 + kstep; const char* b3 = b2 + kstep;
;             int lf_ = EARLY_DRAIN ? __builtin_amdgcn_readfirstlane(landed_flag) : landed_flag; if constexpr (EARLY_DRAIN) asm volatile("" : "+s"(lf_)); landed_flag = 0;
;             PG8_LDB(B0, 0, 0); PG8_LDB(B1, 0, 1); PG8_SCHED; PG8_LDA(At, 0, 0); PG8_STAGE(PG8_SA(1, 1), a1 + ahs, voffA);
;             if (!lf_) PG8_WAIT_V(8);
;             PG8_WAIT_L(0); PG8_BAR; PG8_MMA(0, 0, At, B0); PG8_MMA(0, 1, At, B1); PG8_BAR; PG8_SCHED;
;             PG8_LDA(At, 0, 1); PG8_STAGE(PG8_SB(0, 0), b2, voffB); PG8_STAGE(PG8_SB(0, 1), b2 + bhs, voffB); PG8_STAGE(PG8_SA(0, 0), a2, voffA);
;             if (!lf_) PG8_WAIT_V(8);
;             PG8_WAIT_L(0); PG8_BAR; PG8_MMA(1, 0, At, B0); PG8_MMA(1, 1, At, B1); PG8_BAR; PG8_SCHED;
;             PG8_LDB(B0, 1, 0); PG8_LDB(B1, 1, 1); PG8_SCHED; PG8_LDA(At, 1, 0); PG8_STAGE(PG8_SA(0, 1), a2 + ahs, voffA);
;             if (!lf_) PG8_WAIT_V(8);
.LBB0_737:
	s_waitcnt lgkmcnt(0)
	s_cmp_eq_u32 s0, 40
	s_cselect_b32 s85, s35, s24
	s_cselect_b32 s84, s34, s19
	s_cselect_b32 s71, s77, s26
	s_cselect_b32 s70, s76, s25
	s_barrier
	s_setprio 1
	s_waitcnt lgkmcnt(7)
	v_mfma_f32_16x16x32_bf16 v[98:101], v[158:161], v[126:129], v[162:165]
	v_mfma_f32_16x16x32_bf16 v[114:117], v[170:173], v[126:129], v[154:157]
	s_waitcnt lgkmcnt(5)
	v_mfma_f32_16x16x32_bf16 v[110:113], v[170:173], v[194:197], v[110:113]
	v_mfma_f32_16x16x32_bf16 v[118:121], v[158:161], v[194:197], v[118:121]
	s_waitcnt lgkmcnt(3)
	v_mfma_f32_16x16x32_bf16 v[94:97], v[158:161], v[186:189], v[94:97]
	v_mfma_f32_16x16x32_bf16 v[90:93], v[170:173], v[186:189], v[90:93]
	s_waitcnt lgkmcnt(1)
	v_mfma_f32_16x16x32_bf16 v[74:77], v[170:173], v[178:181], v[74:77]
	v_mfma_f32_16x16x32_bf16 v[78:81], v[158:161], v[178:181], v[78:81]
	v_mfma_f32_16x16x32_bf16 v[98:101], v[166:169], v[202:205], v[98:101]
	v_mfma_f32_16x16x32_bf16 v[114:117], v[174:177], v[202:205], v[114:117]
	v_mfma_f32_16x16x32_bf16 v[110:113], v[174:177], v[198:201], v[110:113]
	v_mfma_f32_16x16x32_bf16 v[118:121], v[166:169], v[198:201], v[118:121]
	v_mfma_f32_16x16x32_bf16 v[94:97], v[166:169], v[190:193], v[94:97]
	v_mfma_f32_16x16x32_bf16 v[90:93], v[174:177], v[190:193], v[90:93]
	s_waitcnt lgkmcnt(0)
	v_mfma_f32_16x16x32_bf16 v[74:77], v[174:177], v[182:185], v[74:77]
	v_mfma_f32_16x16x32_bf16 v[78:81], v[166:169], v[182:185], v[78:81]
	s_setprio 0
	s_setprio 1
	v_mfma_f32_16x16x32_bf16 v[122:125], v[134:137], v[126:129], v[146:149]
	v_mfma_f32_16x16x32_bf16 v[126:129], v[142:145], v[126:129], v[130:133]
	v_mfma_f32_16x16x32_bf16 v[102:105], v[142:145], v[194:197], v[102:105]
	v_mfma_f32_16x16x32_bf16 v[106:109], v[134:137], v[194:197], v[106:109]
	v_mfma_f32_16x16x32_bf16 v[86:89], v[134:137], v[186:189], v[86:89]
	v_mfma_f32_16x16x32_bf16 v[82:85], v[142:145], v[186:189], v[82:85]
	v_mfma_f32_16x16x32_bf16 v[66:69], v[142:145], v[178:181], v[66:69]
	v_mfma_f32_16x16x32_bf16 v[70:73], v[134:137], v[178:181], v[70:73]
	v_mfma_f32_16x16x32_bf16 v[122:125], v[138:141], v[202:205], v[122:125]
	v_mfma_f32_16x16x32_bf16 v[126:129], v[150:153], v[202:205], v[126:129]
	v_mfma_f32_16x16x32_bf16 v[102:105], v[150:153], v[198:201], v[102:105]
	v_mfma_f32_16x16x32_bf16 v[106:109], v[138:141], v[198:201], v[106:109]
	v_mfma_f32_16x16x32_bf16 v[86:89], v[138:141], v[190:193], v[86:89]
	v_mfma_f32_16x16x32_bf16 v[82:85], v[150:153], v[190:193], v[82:85]
	v_mfma_f32_16x16x32_bf16 v[66:69], v[150:153], v[182:185], v[66:69]
	v_mfma_f32_16x16x32_bf16 v[70:73], v[138:141], v[182:185], v[70:73]
	s_setprio 0
	s_barrier
	ds_read_b128 v[186:189], v250 offset:16384
	ds_read_b128 v[190:193], v250 offset:17408
	ds_read_b128 v[178:181], v250 offset:18432
	ds_read_b128 v[182:185], v250 offset:19456
	ds_read_b128 v[154:157], v250 offset:20480
	ds_read_b128 v[162:165], v250 offset:21504
	ds_read_b128 v[130:133], v250 offset:22528
	ds_read_b128 v[146:149], v250 offset:23552
	s_mov_b32 m0, s12
	s_nop 0
	global_load_lds_dwordx4 v230, s[70:71]
	s_add_u32 m0, m0, 0x2000
	s_nop 0
	global_load_lds_dwordx4 v232, s[70:71]
	s_add_u32 s14, s70, 0xb0000
	s_addc_u32 s15, s71, 0
	s_mov_b32 m0, s13
	s_nop 0
	global_load_lds_dwordx4 v230, s[14:15]
	s_add_u32 m0, m0, 0x2000
	s_nop 0
	global_load_lds_dwordx4 v232, s[14:15]
	v_cndmask_b32_e64 v194, 0, 1, s[86:87]
	s_mov_b32 m0, s10
	s_nop 0
	global_load_lds_dwordx4 v0, s[84:85]
	s_add_u32 m0, m0, 0x2000
	s_nop 0
	global_load_lds_dwordx4 v231, s[84:85]
	v_cmp_ne_u32_e64 s[38:39], 1, v194
	s_andn2_b64 vcc, exec, s[86:87]
	s_cbranch_vccnz .LBB0_739
	s_waitcnt vmcnt(8)
.LBB0_739:
	s_waitcnt lgkmcnt(0)
	s_barrier
	s_setprio 1
	s_waitcnt lgkmcnt(7)
	v_mfma_f32_16x16x32_bf16 v[62:65], v[158:161], v[186:189], v[62:65]
	v_mfma_f32_16x16x32_bf16 v[58:61], v[170:173], v[186:189], v[58:61]
	s_waitcnt lgkmcnt(5)
	v_mfma_f32_16x16x32_bf16 v[42:45], v[170:173], v[178:181], v[42:45]
	v_mfma_f32_16x16x32_bf16 v[46:49], v[158:161], v[178:181], v[46:49]
	s_waitcnt lgkmcnt(3)
	v_mfma_f32_16x16x32_bf16 v[30:33], v[158:161], v[154:157], v[30:33]
	v_mfma_f32_16x16x32_bf16 v[26:29], v[170:173], v[154:157], v[26:29]
	s_waitcnt lgkmcnt(1)
	v_mfma_f32_16x16x32_bf16 v[10:13], v[170:173], v[130:133], v[10:13]
	v_mfma_f32_16x16x32_bf16 v[14:17], v[158:161], v[130:133], v[14:17]
	v_mfma_f32_16x16x32_bf16 v[62:65], v[166:169], v[190:193], v[62:65]
	v_mfma_f32_16x16x32_bf16 v[58:61], v[174:177], v[190:193], v[58:61]
	v_mfma_f32_16x16x32_bf16 v[42:45], v[174:177], v[182:185], v[42:45]
	v_mfma_f32_16x16x32_bf16 v[46:49], v[166:169], v[182:185], v[46:49]
	v_mfma_f32_16x16x32_bf16 v[30:33], v[166:169], v[162:165], v[30:33]
	v_mfma_f32_16x16x32_bf16 v[26:29], v[174:177], v[162:165], v[26:29]
	s_waitcnt lgkmcnt(0)
	v_mfma_f32_16x16x32_bf16 v[10:13], v[174:177], v[146:149], v[10:13]
	v_mfma_f32_16x16x32_bf16 v[14:17], v[166:169], v[146:149], v[14:17]
	s_setprio 0
	s_setprio 1
	v_mfma_f32_16x16x32_bf16 v[54:57], v[134:137], v[186:189], v[54:57]
	v_mfma_f32_16x16x32_bf16 v[50:53], v[142:145], v[186:189], v[50:53]
	v_mfma_f32_16x16x32_bf16 v[34:37], v[142:145], v[178:181], v[34:37]
	v_mfma_f32_16x16x32_bf16 v[38:41], v[134:137], v[178:181], v[38:41]
	v_mfma_f32_16x16x32_bf16 v[22:25], v[134:137], v[154:157], v[22:25]
	v_mfma_f32_16x16x32_bf16 v[18:21], v[142:145], v[154:157], v[18:21]
	v_mfma_f32_16x16x32_bf16 v[2:5], v[142:145], v[130:133], v[2:5]
	v_mfma_f32_16x16x32_bf16 v[6:9], v[134:137], v[130:133], v[6:9]
	v_mfma_f32_16x16x32_bf16 v[54:57], v[138:141], v[190:193], v[54:57]
	v_mfma_f32_16x16x32_bf16 v[50:53], v[150:153], v[190:193], v[50:53]
	v_mfma_f32_16x16x32_bf16 v[34:37], v[150:153], v[182:185], v[34:37]
	v_mfma_f32_16x16x32_bf16 v[38:41], v[138:141], v[182:185], v[38:41]
	v_mfma_f32_16x16x32_bf16 v[22:25], v[138:141], v[162:165], v[22:25]
	v_mfma_f32_16x16x32_bf16 v[18:21], v[150:153], v[162:165], v[18:21]
	v_mfma_f32_16x16x32_bf16 v[2:5], v[150:153], v[146:149], v[2:5]
	v_mfma_f32_16x16x32_bf16 v[6:9], v[138:141], v[146:149], v[6:9]
	s_setprio 0
	s_barrier
	ds_read_b128 v[158:161], v244
	ds_read_b128 v[166:169], v244 offset:1024
	ds_read_b128 v[170:173], v244 offset:2048
	ds_read_b128 v[174:177], v244 offset:3072
	ds_read_b128 v[134:137], v245
	ds_read_b128 v[138:141], v245 offset:1024
	ds_read_b128 v[142:145], v245 offset:2048
	ds_read_b128 v[150:153], v245 offset:3072
	ds_read_b128 v[130:133], v250 offset:32768
	ds_read_b128 v[202:205], v250 offset:33792
	ds_read_b128 v[194:197], v250 offset:34816
	ds_read_b128 v[198:201], v250 offset:35840
	ds_read_b128 v[186:189], v250 offset:36864
	ds_read_b128 v[190:193], v250 offset:37888
	ds_read_b128 v[178:181], v250 offset:38912
	ds_read_b128 v[182:185], v250 offset:39936
	s_add_u32 s14, s84, 0xb0000
	s_addc_u32 s15, s85, 0
	s_mov_b32 m0, s99
	s_nop 0
	global_load_lds_dwordx4 v0, s[14:15]
	s_add_u32 m0, m0, 0x2000
	s_nop 0
	global_load_lds_dwordx4 v231, s[14:15]
	s_and_b64 vcc, exec, s[38:39]
	s_cbranch_vccnz .LBB0_734
	s_waitcnt vmcnt(8)
	s_branch .LBB0_734
